# out-phase unit remap + de-serialised staging loads in the three chunk-output kinds + h chunks preloaded in the fused GEMM epilogues
# speedup vs baseline: 1.0235x; 1.0052x over previous
; template <int MX>
; __device__ void out_unit(const P& p, int layer, int unit, char* smem) {
;     ...
;   const int rbase = b * RB + c * 128 - PADB, rpad = RREAL + b * PADB;
;   const float l2g = __log2f(1.f - exp2f(-5.f - (float)h));
;   float mprev = 0.f;
;   constexpr int GC = (MX == 0) ? C_GR : (MX == 1 ? C_MO : C_RG);
;   uint2 gpre[4];
;   {
;     const bf16* gp = p.U() + TROW(16 * w + r) * US + GC + h * 64 + 4 * q4;
; #pragma unroll
;     for (int et = 0; et < 4; ++et) gpre[et] = *(const uint2*)(gp + 16 * et);
;   }
;   __syncthreads();
;   {
;     const int t = tid >> 2;
;     if (MX == 0) {
;       const int d0 = (tid & 3) * 8;
;       *(uint4*)(Qs + t * 72 + d0) = *(const uint4*)(p.U() + TROW(t) * US + C_GQ + h * 32 + d0);
;       *(uint4*)(Ks + t * 72 + d0) = *(const uint4*)(p.U() + TROW(t) * US + C_GK + h * 32 + d0);
;     } else {
;       const int d0 = (tid & 3) * 16;
;       const bf16* qs = (MX == 1) ? (p.mlqk() + TROW(t) * 512 + h * 128 + d0) : (p.U() + TROW(t) * US + C_RQ + h * 64 + d0);
;       const bf16* ks = (MX == 1) ? (p.mlqk() + TROW(t) * 512 + h * 128 + 64 + d0) : (p.U() + TROW(t) * US + C_RK + h * 64 + d0);
;       *(uint4*)(Qs + t * 72 + d0) = *(const uint4*)qs;
;       *(uint4*)(Qs + t * 72 + d0 + 8) = *(const uint4*)(qs + 8);
;       *(uint4*)(Ks + t * 72 + d0) = *(const uint4*)ks;
;       *(uint4*)(Ks + t * 72 + d0 + 8) = *(const uint4*)(ks + 8);
;     }
;     {
;       const int e0 = (tid >> 7) * 16;
;       const int t = tid & 127;
;       constexpr int VC = (MX == 0) ? C_GV : (MX == 1 ? C_MV : C_RV);
;       const bf16* vs = p.U() + TROW(t) * US + VC + h * 64 + e0;
;       const uint4 v0 = *(const uint4*)vs, v1 = *(const uint4*)(vs + 8);
;       Vt[(e0 + 0) * 136 + t] = (bf16)(v0.x & 0xffffu); Vt[(e0 + 1) * 136 + t] = (bf16)(v0.x >> 16);
;       Vt[(e0 + 2) * 136 + t] = (bf16)(v0.y & 0xffffu); Vt[(e0 + 3) * 136 + t] = (bf16)(v0.y >> 16);
;       Vt[(e0 + 4) * 136 + t] = (bf16)(v0.z & 0xffffu); Vt[(e0 + 5) * 136 + t] = (bf16)(v0.z >> 16);
;       Vt[(e0 + 6) * 136 + t] = (bf16)(v0.w & 0xffffu); Vt[(e0 + 7) * 136 + t] = (bf16)(v0.w >> 16);
;       Vt[(e0 + 8) * 136 + t] = (bf16)(v1.x & 0xffffu); Vt[(e0 + 9) * 136 + t] = (bf16)(v1.x >> 16);
;       Vt[(e0 + 10) * 136 + t] = (bf16)(v1.y & 0xffffu); Vt[(e0 + 11) * 136 + t] = (bf16)(v1.y >> 16);
.LBB0_485:
	s_cmpk_lt_i32 s33, 0x618
	s_mov_b64 s[0:1], -1
	s_cbranch_scc0 .LBB0_526
	s_mul_hi_i32 s0, s33, 0x7e07e07f
	s_lshr_b32 s1, s0, 31
	s_ashr_i32 s0, s0, 8
	s_add_i32 s0, s0, s1
	s_mulk_i32 s0, 0x208
	s_sub_i32 s6, s33, s0
	s_add_i32 s0, s33, 0x207
	s_cmpk_gt_u32 s0, 0x40e
	s_mov_b64 s[0:1], -1
	s_cbranch_scc0 .LBB0_508
	s_add_i32 s0, s33, 0xfffffdf8
	s_cmpk_gt_u32 s0, 0x207
	s_mov_b64 s[0:1], -1
	s_cbranch_scc0 .LBB0_504
	s_sext_i32_i16 s0, s6
	s_mulk_i32 s0, 0xfc1
	s_lshr_b32 s1, s0, 31
	s_ashr_i32 s0, s0, 18
	s_add_i32 s0, s0, s1
	s_mul_i32 s1, s0, 0x41
	s_sext_i32_i16 s0, s0
	s_and_b32 s14, s0, 3
	s_ashr_i32 s0, s0, 2
	v_cvt_f32_ubyte0_e32 v0, s14
	s_mul_i32 s3, s0, 0x2010
	s_mul_i32 s13, s0, 0x70
	v_sub_f32_e32 v0, 0xc0a00000, v0
	s_mov_b32 s0, 0xc2fc0000
	s_sub_i32 s2, s6, s1
	v_cmp_gt_f32_e32 vcc, s0, v0
	s_sext_i32_i16 s1, s2
	s_lshl_b32 s1, s1, 7
	v_cndmask_b32_e32 v1, 0, v194, vcc
	v_add_f32_e32 v0, v0, v1
	s_add_i32 s12, s1, s3
	v_exp_f32_e32 v0, v0
	s_addk_i32 s12, 0xff90
	s_addk_i32 s13, 0x4020
	s_and_b64 s[0:1], vcc, exec
	s_cselect_b32 s0, 0xffffffc0, 0
	v_mov_b32_e32 v3, v136
	v_ldexp_f32 v0, v0, s0
	s_mov_b32 s0, 0x6180000
	v_sub_f32_e32 v0, 1.0, v0
	v_ashrrev_i32_e32 v2, 6, v3
	s_add_u32 s0, s76, s0
	v_and_b32_e32 v25, 15, v3
	v_log_f32_e32 v24, v0
	s_addc_u32 s1, s77, 0
	s_and_b32 s2, s2, 0xffff
	v_lshlrev_b32_e32 v0, 4, v2
	s_cmp_eq_u32 s2, 0
	v_or_b32_e32 v26, v0, v25
	s_movk_i32 s7, 0x70
	s_cselect_b64 s[2:3], -1, 0
	v_cmp_gt_i32_e32 vcc, s7, v26
	v_or_b32_e32 v1, s12, v25
	s_and_b64 vcc, s[2:3], vcc
	v_add_u32_e32 v0, v1, v0
	v_add_u32_e32 v1, s13, v26
	v_cndmask_b32_e32 v6, v0, v1, vcc
	v_mov_b64_e32 v[0:1], s[0:1]
	v_bfe_u32 v4, v3, 4, 2
	v_mad_i64_i32 v[0:1], s[0:1], v6, s54, v[0:1]
	s_lshl_b32 s96, s14, 7
	v_lshl_add_u64 v[0:1], v[0:1], 0, s[96:97]
	v_lshlrev_b32_e32 v138, 3, v4
	v_lshl_add_u64 v[0:1], v[0:1], 0, v[138:139]
	s_mov_b64 s[0:1], 0x1a30
	s_movk_i32 s8, 0x1000
	v_lshl_add_u64 v[6:7], v[0:1], 0, s[0:1]
	v_add_co_u32_e64 v0, s[0:1], s8, v0
	v_ashrrev_i32_e32 v28, 2, v3
	s_nop 0
	v_addc_co_u32_e64 v1, s[0:1], 0, v1, s[0:1]
	s_mov_b32 s0, 0x6180000
	global_load_dwordx2 v[22:23], v[0:1], off offset:2608
	global_load_dwordx2 v[20:21], v[6:7], off offset:32
	global_load_dwordx2 v[18:19], v[6:7], off offset:64
	global_load_dwordx2 v[16:17], v[6:7], off offset:96
	s_barrier
	s_add_u32 s4, s76, s0
	v_cmp_gt_i32_e64 s[0:1], s7, v28
	s_addc_u32 s5, s77, 0
	s_and_b64 s[0:1], s[2:3], s[0:1]
	v_mov_b32_e32 v29, s12
	v_mov_b32_e32 v30, s13
	v_cndmask_b32_e64 v0, v29, v30, s[0:1]
	v_add_u32_e32 v12, v0, v28
	v_mov_b64_e32 v[0:1], s[4:5]
	v_mad_i64_i32 v[0:1], s[0:1], v12, s54, v[0:1]
	v_lshlrev_b32_e32 v6, 5, v3
	v_lshl_add_u64 v[0:1], v[0:1], 0, s[96:97]
	v_and_b32_e32 v6, 0x60, v6
	v_mov_b32_e32 v7, v139
	v_lshl_add_u64 v[0:1], v[0:1], 0, v[6:7]
	s_mov_b64 s[0:1], 0x1430
	v_lshl_add_u64 v[10:11], v[0:1], 0, s[0:1]
	s_mov_b32 s0, 0x6180000
	s_add_u32 s0, s76, s0
	s_addc_u32 s1, s77, 0
	v_mov_b64_e32 v[8:9], s[0:1]
	v_mad_i64_i32 v[8:9], s[0:1], v12, s54, v[8:9]
	v_lshl_add_u64 v[8:9], v[8:9], 0, s[96:97]
	v_lshl_add_u64 v[12:13], v[8:9], 0, v[6:7]
	s_mov_b64 s[0:1], 0x1630
	v_lshl_add_u64 v[14:15], v[12:13], 0, s[0:1]
	v_add_co_u32_e64 v0, s[0:1], s8, v0
	v_mul_lo_u32 v7, v28, s50
	s_nop 0
	v_addc_co_u32_e64 v1, s[0:1], 0, v1, s[0:1]
	v_add3_u32 v28, s45, v7, v6
	global_load_dwordx4 v[222:225], v[0:1], off offset:1072
	v_add_co_u32_e64 v0, s[0:1], s8, v12
	v_and_b32_e32 v5, 63, v3
	s_nop 0
	v_addc_co_u32_e64 v1, s[0:1], 0, v13, s[0:1]
	s_mov_b32 s0, 0x6180000
	v_lshlrev_b32_e32 v27, 2, v4
	s_movk_i32 s44, 0x70
	s_movk_i32 s10, 0x1000
	s_movk_i32 s15, 0x110
	global_load_dwordx4 v[210:213], v[10:11], off offset:16
	global_load_dwordx4 v[214:217], v[0:1], off offset:1584
	global_load_dwordx4 v[218:221], v[14:15], off offset:16
	v_and_b32_e32 v15, 0x7f, v3
	v_ashrrev_i32_e32 v14, 3, v3
	v_and_b32_e32 v0, -16, v14
	s_add_u32 s4, s76, s0
	v_cmp_gt_u32_e64 s[0:1], s7, v15
	s_addc_u32 s5, s77, 0
	s_and_b64 s[0:1], s[2:3], s[0:1]
	v_cndmask_b32_e64 v1, v29, v30, s[0:1]
	v_add_u32_e32 v1, v1, v15
	v_mov_b64_e32 v[6:7], s[4:5]
	v_mad_i64_i32 v[6:7], s[0:1], v1, s54, v[6:7]
	v_lshl_add_u64 v[6:7], v[6:7], 0, s[96:97]
	v_ashrrev_i32_e32 v1, 31, v0
	v_lshl_add_u64 v[6:7], v[0:1], 1, v[6:7]
	s_mov_b64 s[0:1], 0x1830
	v_lshl_add_u64 v[10:11], v[6:7], 0, s[0:1]
	v_add_co_u32_e64 v6, s[0:1], s8, v6
	v_lshlrev_b32_e32 v1, 1, v15
	s_nop 0
	v_addc_co_u32_e64 v7, s[0:1], 0, v7, s[0:1]
	global_load_dwordx4 v[226:229], v[6:7], off offset:2096
	s_nop 0
	global_load_dwordx4 v[230:233], v[10:11], off offset:16
	s_movk_i32 s0, 0x110
	v_mul_lo_u32 v0, v0, s0
	v_add3_u32 v242, s45, v0, v1
	v_or_b32_e32 v0, 15, v14
	v_mul_lo_u32 v0, v0, s0
	v_add3_u32 v243, s45, v0, v1
	s_mov_b32 s0, 0x1b7e8700
	s_add_u32 s2, s76, s0
	s_addc_u32 s3, s77, 0
	s_ashr_i32 s7, s6, 31
	s_lshl_b64 s[0:1], s[6:7], 14
	s_add_u32 s0, s2, s0
	v_lshlrev_b32_e32 v0, 3, v2
	s_addc_u32 s1, s3, s1
	v_lshlrev_b32_e32 v6, 8, v5
	v_mov_b32_e32 v7, v139
	v_lshl_add_u64 v[6:7], s[0:1], 0, v[6:7]
	v_ashrrev_i32_e32 v1, 31, v0
	v_lshl_add_u64 v[0:1], v[0:1], 2, v[6:7]
	global_load_dwordx4 v[234:237], v[0:1], off offset:16
	global_load_dwordx4 v[238:241], v[0:1], off
	s_movk_i32 s0, 0x480
	v_mul_lo_u32 v1, v2, s0
	v_lshlrev_b32_e32 v5, 1, v5
	v_readlane_b32 s0, v254, 57
	s_waitcnt vmcnt(7)
	ds_write_b128 v28, v[222:225]
	s_waitcnt vmcnt(6)
	ds_write_b128 v28, v[210:213] offset:16
	s_waitcnt vmcnt(5)
	ds_write_b128 v28, v[214:217] offset:18432
	s_waitcnt vmcnt(4)
	ds_write_b128 v28, v[218:221] offset:18448
	s_waitcnt vmcnt(3)
; template <int MX>
; __device__ void out_unit(const P& p, int layer, int unit, char* smem) {
;     ...
;       Vt[(e0 + 0) * 136 + t] = (bf16)(v0.x & 0xffffu); Vt[(e0 + 1) * 136 + t] = (bf16)(v0.x >> 16);
;       Vt[(e0 + 2) * 136 + t] = (bf16)(v0.y & 0xffffu); Vt[(e0 + 3) * 136 + t] = (bf16)(v0.y >> 16);
;       Vt[(e0 + 4) * 136 + t] = (bf16)(v0.z & 0xffffu); Vt[(e0 + 5) * 136 + t] = (bf16)(v0.z >> 16);
;       Vt[(e0 + 6) * 136 + t] = (bf16)(v0.w & 0xffffu); Vt[(e0 + 7) * 136 + t] = (bf16)(v0.w >> 16);
;       Vt[(e0 + 8) * 136 + t] = (bf16)(v1.x & 0xffffu); Vt[(e0 + 9) * 136 + t] = (bf16)(v1.x >> 16);
;       Vt[(e0 + 10) * 136 + t] = (bf16)(v1.y & 0xffffu); Vt[(e0 + 11) * 136 + t] = (bf16)(v1.y >> 16);
;       Vt[(e0 + 12) * 136 + t] = (bf16)(v1.z & 0xffffu); Vt[(e0 + 13) * 136 + t] = (bf16)(v1.z >> 16);
;       Vt[(e0 + 14) * 136 + t] = (bf16)(v1.w & 0xffffu); Vt[(e0 + 15) * 136 + t] = (bf16)(v1.w >> 16);
;     }
;     if (MX == 0) {
;       const int d = tid & 31, e0 = (tid >> 5) * 4;
;       const float4 s4 = *(const float4*)(p.gla_loc() + ((size_t)unit * 32 + d) * 64 + e0);
;       St[(e0 + 0) * 72 + d] = f2bf(s4.x); St[(e0 + 1) * 72 + d] = f2bf(s4.y); St[(e0 + 2) * 72 + d] = f2bf(s4.z); St[(e0 + 3) * 72 + d] = f2bf(s4.w);
;     } else {
;       const int d = tid & 63, e0 = (tid >> 6) * 8;
;       const float* sp = ((MX == 1) ? p.ml_c() : p.ret_loc()) + ((size_t)unit * 64 + d) * 64 + e0;
;       const float4 s4 = *(const float4*)sp, s5 = *(const float4*)(sp + 4);
;       St[(e0 + 0) * 72 + d] = f2bf(s4.x); St[(e0 + 1) * 72 + d] = f2bf(s4.y); St[(e0 + 2) * 72 + d] = f2bf(s4.z); St[(e0 + 3) * 72 + d] = f2bf(s4.w);
;       St[(e0 + 4) * 72 + d] = f2bf(s5.x); St[(e0 + 5) * 72 + d] = f2bf(s5.y); St[(e0 + 6) * 72 + d] = f2bf(s5.z); St[(e0 + 7) * 72 + d] = f2bf(s5.w);
;     ...
;   const int ktmax = w | 1;
; #pragma unroll
;   for (int kt = 0; kt < 8; ++kt) {
;     if (kt <= ktmax) {
;       f32x4 s = f32x4{0.f, 0.f, 0.f, 0.f};
; #pragma unroll
;       for (int kb = 0; kb < DK / 32; ++kb) {
;         const bf16x8 a = *(const bf16x8*)(Qs + (16 * w + r) * 72 + kb * 32 + q4 * 8);
;         const bf16x8 bq = *(const bf16x8*)(Ks + (16 * kt + r) * 72 + kb * 32 + q4 * 8);
;         s = MFMA(bq, a, s);
;       }
;       const int qq = 16 * w + r;
;       const float vaq = (MX == 1) ? va[qq] : 0.f;
;       float sw[4];
; #pragma unroll
;       for (int j = 0; j < 4; ++j) {
	ds_write_b16 v242, v226 offset:36864
	ds_write_b16_d16_hi v242, v226 offset:37136
	ds_write_b16 v242, v227 offset:37408
	ds_write_b16_d16_hi v242, v227 offset:37680
	ds_write_b16 v242, v228 offset:37952
	ds_write_b16_d16_hi v242, v228 offset:38224
	ds_write_b16 v242, v229 offset:38496
	ds_write_b16_d16_hi v242, v229 offset:38768
	s_waitcnt vmcnt(2)
	ds_write_b16 v242, v230 offset:39040
	ds_write_b16_d16_hi v242, v230 offset:39312
	ds_write_b16 v242, v231 offset:39584
	ds_write_b16_d16_hi v242, v231 offset:39856
	ds_write_b16 v242, v232 offset:40128
	ds_write_b16_d16_hi v242, v232 offset:40400
	ds_write_b16 v242, v233 offset:40672
	ds_write_b16_d16_hi v243, v233 offset:36864
	s_waitcnt vmcnt(0)
	v_cvt_pk_bf16_f32 v0, v238, v139
	s_nop 0
	v_add3_u32 v1, s0, v1, v5
	ds_write_b16 v1, v0
	v_cvt_pk_bf16_f32 v0, v239, v139
	ds_write_b16 v1, v0 offset:144
	v_cvt_pk_bf16_f32 v0, v240, v139
	ds_write_b16 v1, v0 offset:288
	v_cvt_pk_bf16_f32 v0, v241, v139
	ds_write_b16 v1, v0 offset:432
	v_cvt_pk_bf16_f32 v0, v234, v139
	ds_write_b16 v1, v0 offset:576
	v_cvt_pk_bf16_f32 v0, v235, v139
	ds_write_b16 v1, v0 offset:720
	v_cvt_pk_bf16_f32 v0, v236, v139
	ds_write_b16 v1, v0 offset:864
	v_cvt_pk_bf16_f32 v0, v237, v139
	ds_write_b16 v1, v0 offset:1008
	v_mov_b32_e32 v6, v234
	v_mov_b32_e32 v7, v235
	v_mov_b32_e32 v8, v236
	v_mov_b32_e32 v9, v237
	v_mov_b32_e32 v10, v238
	v_mov_b32_e32 v11, v239
	v_mov_b32_e32 v12, v240
	v_mov_b32_e32 v13, v241
	v_mul_lo_u32 v0, v26, s50
	v_add_u32_e32 v0, 0x100, v0
	v_and_b32_e32 v1, 48, v3
	v_add_u32_e32 v28, v0, v1
	v_add_u32_e32 v1, 0x100, v1
	v_lshlrev_b32_e32 v3, 7, v26
	v_add3_u32 v0, v0, v3, v138
	v_cmp_lt_i32_e64 s[2:3], -1, v2
	v_mad_u32_u24 v1, v25, s50, v1
	s_waitcnt lgkmcnt(0)
	s_barrier
	s_and_saveexec_b64 s[8:9], s[2:3]
	s_cbranch_execz .LBB0_490
	v_sub_u32_e32 v3, v26, v27
	v_cvt_f32_i32_e32 v3, v3
	ds_read_b128 v[6:9], v28
	ds_read_b128 v[10:13], v1 offset:18432
	s_mov_b32 s7, 0xc2fc0000
	s_waitcnt lgkmcnt(0)
	v_mfma_f32_16x16x32_bf16 v[6:9], v[10:13], v[6:9], 0
	v_mul_f32_e32 v5, v24, v3
	v_cmp_gt_f32_e64 s[0:1], s7, v5
	ds_read_b128 v[10:13], v28 offset:64
	ds_read_b128 v[30:33], v1 offset:18496
	v_cndmask_b32_e64 v5, 0, v194, s[0:1]
	v_fmac_f32_e32 v5, v24, v3
	v_exp_f32_e32 v3, v5
	v_cndmask_b32_e64 v5, 0, v195, s[0:1]
	s_waitcnt lgkmcnt(0)
	v_mfma_f32_16x16x32_bf16 v[6:9], v[30:33], v[10:13], v[6:9]
	v_cmp_ge_i32_e64 s[0:1], v26, v27
	v_ldexp_f32 v3, v3, v5
	v_xad_u32 v5, v27, -1, v26
	v_cvt_f32_i32_e32 v5, v5
	v_cndmask_b32_e64 v3, 0, v3, s[0:1]
	s_nop 2
	v_mul_f32_e32 v3, v3, v6
	v_cmp_gt_i32_e64 s[0:1], v26, v27
	v_mul_f32_e32 v6, v24, v5
	v_cmp_gt_f32_e64 s[4:5], s7, v6
	s_nop 1
	v_cndmask_b32_e64 v6, 0, v194, s[4:5]
	v_fmac_f32_e32 v6, v24, v5
	v_exp_f32_e32 v5, v6
	v_cndmask_b32_e64 v6, 0, v195, s[4:5]
	v_ldexp_f32 v5, v5, v6
	v_cndmask_b32_e64 v5, 0, v5, s[0:1]
	v_or_b32_e32 v6, 2, v27
	v_mul_f32_e32 v5, v5, v7
	v_sub_u32_e32 v7, v26, v6
	v_cvt_f32_i32_e32 v7, v7
	v_mul_f32_e32 v10, v24, v7
	v_cmp_gt_f32_e64 s[0:1], s7, v10
	s_nop 1
	v_cndmask_b32_e64 v10, 0, v194, s[0:1]
	v_fmac_f32_e32 v10, v24, v7
	v_exp_f32_e32 v7, v10
	v_cndmask_b32_e64 v10, 0, v195, s[0:1]
	v_cmp_ge_i32_e64 s[0:1], v26, v6
	v_ldexp_f32 v7, v7, v10
	s_nop 0
	v_cndmask_b32_e64 v6, 0, v7, s[0:1]
	v_mul_f32_e32 v7, v6, v8
	v_or_b32_e32 v6, 3, v27
	v_sub_u32_e32 v8, v26, v6
	v_cvt_f32_i32_e32 v8, v8
	v_mul_f32_e32 v10, v24, v8
	v_cmp_gt_f32_e64 s[0:1], s7, v10
	s_nop 1
	v_cndmask_b32_e64 v10, 0, v194, s[0:1]
	v_fmac_f32_e32 v10, v24, v8
	v_exp_f32_e32 v8, v10
	v_cndmask_b32_e64 v10, 0, v195, s[0:1]
	v_cmp_ge_i32_e64 s[0:1], v26, v6
	v_ldexp_f32 v8, v8, v10
	s_nop 0
	v_cndmask_b32_e64 v6, 0, v8, s[0:1]
	v_mul_f32_e32 v8, v6, v9
	v_cvt_pk_bf16_f32 v6, v3, v5
	v_cvt_pk_bf16_f32 v7, v7, v8
	ds_write_b64 v0, v[6:7] offset:58624
	ds_read_b128 v[6:9], v28
	ds_read_b128 v[10:13], v1 offset:20736
	v_or_b32_e32 v3, 16, v27
	s_waitcnt lgkmcnt(0)
	v_mfma_f32_16x16x32_bf16 v[6:9], v[10:13], v[6:9], 0
	ds_read_b128 v[10:13], v28 offset:64
	ds_read_b128 v[30:33], v1 offset:20800
	v_sub_u32_e32 v5, v26, v3
	v_cvt_f32_i32_e32 v5, v5
	s_waitcnt lgkmcnt(0)
	v_mfma_f32_16x16x32_bf16 v[6:9], v[30:33], v[10:13], v[6:9]
	v_mul_f32_e32 v10, v24, v5
	v_cmp_gt_f32_e64 s[0:1], s7, v10
	s_nop 1
	v_cndmask_b32_e64 v10, 0, v194, s[0:1]
	v_fmac_f32_e32 v10, v24, v5
	v_exp_f32_e32 v5, v10
	v_cndmask_b32_e64 v10, 0, v195, s[0:1]
	v_cmp_ge_i32_e64 s[0:1], v26, v3
	v_ldexp_f32 v5, v5, v10
	s_nop 0
	v_cndmask_b32_e64 v3, 0, v5, s[0:1]
	v_or_b32_e32 v5, 17, v27
	v_mul_f32_e32 v3, v3, v6
	v_sub_u32_e32 v6, v26, v5
	v_cvt_f32_i32_e32 v6, v6
	v_mul_f32_e32 v10, v24, v6
	v_cmp_gt_f32_e64 s[0:1], s7, v10
	s_nop 1
	v_cndmask_b32_e64 v10, 0, v194, s[0:1]
	v_fmac_f32_e32 v10, v24, v6
	v_exp_f32_e32 v6, v10
	v_cndmask_b32_e64 v10, 0, v195, s[0:1]
	v_cmp_ge_i32_e64 s[0:1], v26, v5
	v_ldexp_f32 v6, v6, v10
	s_nop 0
	v_cndmask_b32_e64 v5, 0, v6, s[0:1]
	v_or_b32_e32 v6, 18, v27
	v_mul_f32_e32 v5, v5, v7
	v_sub_u32_e32 v7, v26, v6
	v_cvt_f32_i32_e32 v7, v7
	v_mul_f32_e32 v10, v24, v7
	v_cmp_gt_f32_e64 s[0:1], s7, v10
	s_nop 1
	v_cndmask_b32_e64 v10, 0, v194, s[0:1]
	v_fmac_f32_e32 v10, v24, v7
	v_exp_f32_e32 v7, v10
	v_cndmask_b32_e64 v10, 0, v195, s[0:1]
	v_cmp_ge_i32_e64 s[0:1], v26, v6
	v_ldexp_f32 v7, v7, v10
	s_nop 0
	v_cndmask_b32_e64 v6, 0, v7, s[0:1]
	v_mul_f32_e32 v7, v6, v8
	v_or_b32_e32 v6, 19, v27
	v_sub_u32_e32 v8, v26, v6
	v_cvt_f32_i32_e32 v8, v8
	v_mul_f32_e32 v10, v24, v8
	v_cmp_gt_f32_e64 s[0:1], s7, v10
	s_nop 1
	v_cndmask_b32_e64 v10, 0, v194, s[0:1]
	v_fmac_f32_e32 v10, v24, v8
	v_exp_f32_e32 v8, v10
	v_cndmask_b32_e64 v10, 0, v195, s[0:1]
	v_cmp_ge_i32_e64 s[0:1], v26, v6
	v_ldexp_f32 v8, v8, v10
	s_nop 0
	v_cndmask_b32_e64 v6, 0, v8, s[0:1]
	v_mul_f32_e32 v8, v6, v9
	v_cvt_pk_bf16_f32 v6, v3, v5
	v_cvt_pk_bf16_f32 v7, v7, v8
	ds_write_b64 v0, v[6:7] offset:58656

; template <int MX>
; __device__ void out_unit(const P& p, int layer, int unit, char* smem) {
;     ...
;   uint2 gpre[4];
;   {
;     const bf16* gp = p.U() + TROW(16 * w + r) * US + GC + h * 64 + 4 * q4;
; #pragma unroll
;     for (int et = 0; et < 4; ++et) gpre[et] = *(const uint2*)(gp + 16 * et);
;   }
;   __syncthreads();
;   {
;     const int t = tid >> 2;
;     if (MX == 0) {
;       const int d0 = (tid & 3) * 8;
;       *(uint4*)(Qs + t * 72 + d0) = *(const uint4*)(p.U() + TROW(t) * US + C_GQ + h * 32 + d0);
;       *(uint4*)(Ks + t * 72 + d0) = *(const uint4*)(p.U() + TROW(t) * US + C_GK + h * 32 + d0);
;     } else {
;       const int d0 = (tid & 3) * 16;
;       const bf16* qs = (MX == 1) ? (p.mlqk() + TROW(t) * 512 + h * 128 + d0) : (p.U() + TROW(t) * US + C_RQ + h * 64 + d0);
;       const bf16* ks = (MX == 1) ? (p.mlqk() + TROW(t) * 512 + h * 128 + 64 + d0) : (p.U() + TROW(t) * US + C_RK + h * 64 + d0);
;       *(uint4*)(Qs + t * 72 + d0) = *(const uint4*)qs;
;       *(uint4*)(Qs + t * 72 + d0 + 8) = *(const uint4*)(qs + 8);
;       *(uint4*)(Ks + t * 72 + d0) = *(const uint4*)ks;
;       *(uint4*)(Ks + t * 72 + d0 + 8) = *(const uint4*)(ks + 8);
;     }
;     {
;       const int e0 = (tid >> 7) * 16;
;       const int t = tid & 127;
;       constexpr int VC = (MX == 0) ? C_GV : (MX == 1 ? C_MV : C_RV);
;       const bf16* vs = p.U() + TROW(t) * US + VC + h * 64 + e0;
;       const uint4 v0 = *(const uint4*)vs, v1 = *(const uint4*)(vs + 8);
;       Vt[(e0 + 0) * 136 + t] = (bf16)(v0.x & 0xffffu); Vt[(e0 + 1) * 136 + t] = (bf16)(v0.x >> 16);
;       Vt[(e0 + 2) * 136 + t] = (bf16)(v0.y & 0xffffu); Vt[(e0 + 3) * 136 + t] = (bf16)(v0.y >> 16);
;       Vt[(e0 + 4) * 136 + t] = (bf16)(v0.z & 0xffffu); Vt[(e0 + 5) * 136 + t] = (bf16)(v0.z >> 16);
;       Vt[(e0 + 6) * 136 + t] = (bf16)(v0.w & 0xffffu); Vt[(e0 + 7) * 136 + t] = (bf16)(v0.w >> 16);
;       Vt[(e0 + 8) * 136 + t] = (bf16)(v1.x & 0xffffu); Vt[(e0 + 9) * 136 + t] = (bf16)(v1.x >> 16);
;       Vt[(e0 + 10) * 136 + t] = (bf16)(v1.y & 0xffffu); Vt[(e0 + 11) * 136 + t] = (bf16)(v1.y >> 16);
;       Vt[(e0 + 12) * 136 + t] = (bf16)(v1.z & 0xffffu); Vt[(e0 + 13) * 136 + t] = (bf16)(v1.z >> 16);
;       Vt[(e0 + 14) * 136 + t] = (bf16)(v1.w & 0xffffu); Vt[(e0 + 15) * 136 + t] = (bf16)(v1.w >> 16);
;     }
;     if (MX == 0) {
;       const int d = tid & 31, e0 = (tid >> 5) * 4;
.LBB0_509:
	s_sext_i32_i16 s0, s6
	s_mulk_i32 s0, 0xfc1
	s_lshr_b32 s1, s0, 31
	s_ashr_i32 s0, s0, 18
	s_add_i32 s0, s0, s1
	s_mul_i32 s1, s0, 0x41
	s_sub_i32 s2, s6, s1
	s_sext_i32_i16 s0, s0
	s_sext_i32_i16 s1, s2
	s_and_b32 s4, s0, 3
	s_ashr_i32 s0, s0, 2
	s_mul_i32 s3, s0, 0x2010
	s_lshl_b32 s1, s1, 7
	v_mov_b32_e32 v12, v136
	s_add_i32 s8, s1, s3
	s_mul_i32 s9, s0, 0x70
	s_mov_b32 s0, 0x6180000
	s_addk_i32 s8, 0xff90
	s_addk_i32 s9, 0x4020
	v_ashrrev_i32_e32 v2, 6, v12
	s_add_u32 s0, s76, s0
	v_and_b32_e32 v24, 15, v12
	s_addc_u32 s1, s77, 0
	s_and_b32 s2, s2, 0xffff
	v_lshlrev_b32_e32 v0, 4, v2
	s_cmp_eq_u32 s2, 0
	v_or_b32_e32 v32, v0, v24
	s_movk_i32 s7, 0x70
	s_cselect_b64 s[2:3], -1, 0
	v_cmp_gt_i32_e32 vcc, s7, v32
	v_or_b32_e32 v1, s8, v24
	s_and_b64 vcc, s[2:3], vcc
	v_add_u32_e32 v0, v1, v0
	v_add_u32_e32 v1, s9, v32
	v_cndmask_b32_e32 v4, v0, v1, vcc
	v_mov_b64_e32 v[0:1], s[0:1]
	v_bfe_u32 v3, v12, 4, 2
	v_mad_i64_i32 v[0:1], s[0:1], v4, s54, v[0:1]
	s_lshl_b32 s96, s4, 6
	s_lshl_b32 s4, s4, 7
	s_mov_b32 s5, s97
	v_lshl_add_u64 v[0:1], v[0:1], 0, s[4:5]
	v_lshlrev_b32_e32 v138, 3, v3
	v_lshl_add_u64 v[0:1], v[0:1], 0, v[138:139]
	s_mov_b32 s0, 0x6180000
	global_load_dwordx2 v[22:23], v[0:1], off offset:2560
	global_load_dwordx2 v[20:21], v[0:1], off offset:2592
	global_load_dwordx2 v[18:19], v[0:1], off offset:2624
	global_load_dwordx2 v[16:17], v[0:1], off offset:2656
	s_barrier
	v_ashrrev_i32_e32 v4, 2, v12
	s_add_u32 s12, s76, s0
	v_cmp_gt_i32_e64 s[0:1], s7, v4
	s_addc_u32 s13, s77, 0
	s_and_b64 s[0:1], s[2:3], s[0:1]
	v_mov_b32_e32 v10, s8
	v_mov_b32_e32 v11, s9
	v_cndmask_b32_e64 v0, v10, v11, s[0:1]
	v_add_u32_e32 v13, v0, v4
	v_mov_b64_e32 v[0:1], s[12:13]
	v_mad_i64_i32 v[0:1], s[0:1], v13, s54, v[0:1]
	v_lshlrev_b32_e32 v5, 4, v12
	v_lshl_add_u64 v[0:1], v[0:1], 0, s[96:97]
	v_and_b32_e32 v8, 48, v5
	v_mov_b32_e32 v9, v139
	v_lshl_add_u64 v[0:1], v[0:1], 0, v[8:9]
	v_mul_lo_u32 v4, v4, s50
	v_add3_u32 v14, s45, v4, v8
	v_mov_b32_e32 v245, v14
	global_load_dwordx4 v[222:225], v[0:1], off offset:1536
	s_mov_b32 s0, 0x6180000
	v_lshlrev_b32_e32 v33, 2, v3
	s_movk_i32 s44, 0x70
	s_add_u32 s0, s76, s0
	s_addc_u32 s1, s77, 0
	v_mov_b64_e32 v[0:1], s[0:1]
	v_mad_i64_i32 v[0:1], s[0:1], v13, s54, v[0:1]
	v_lshl_add_u64 v[0:1], v[0:1], 0, s[96:97]
	v_lshl_add_u64 v[0:1], v[0:1], 0, v[8:9]
	global_load_dwordx4 v[210:213], v[0:1], off offset:1792
	s_mov_b32 s0, 0x6180000
	v_ashrrev_i32_e32 v13, 3, v12
	v_and_b32_e32 v0, -16, v13
	v_and_b32_e32 v14, 0x7f, v12
	s_add_u32 s12, s76, s0
	v_cmp_gt_u32_e64 s[0:1], s7, v14
	s_addc_u32 s13, s77, 0
	s_and_b64 s[0:1], s[2:3], s[0:1]
	v_cndmask_b32_e64 v1, v10, v11, s[0:1]
	v_add_u32_e32 v1, v1, v14
	v_mov_b64_e32 v[4:5], s[12:13]
	v_mad_i64_i32 v[4:5], s[0:1], v1, s54, v[4:5]
	v_lshl_add_u64 v[4:5], v[4:5], 0, s[4:5]
	v_ashrrev_i32_e32 v1, 31, v0
	v_lshl_add_u64 v[8:9], v[0:1], 1, v[4:5]
	global_load_dwordx4 v[226:229], v[8:9], off offset:2064
	s_nop 0
	global_load_dwordx4 v[230:233], v[8:9], off offset:2048
	s_movk_i32 s0, 0x110
	v_mul_lo_u32 v0, v0, s0
	v_lshlrev_b32_e32 v1, 1, v14
	v_add3_u32 v242, s45, v0, v1
	s_movk_i32 s12, 0x110
	v_or_b32_e32 v0, 15, v13
	v_mul_lo_u32 v0, v0, s0
	v_add3_u32 v243, s45, v0, v1
	s_mov_b32 s0, 0x1aac3000
	s_add_u32 s2, s76, s0
	s_addc_u32 s3, s77, 0
	s_ashr_i32 s7, s6, 31
	s_lshl_b64 s[0:1], s[6:7], 13
	v_and_b32_e32 v8, 31, v12
	s_add_u32 s0, s2, s0
	v_and_b32_e32 v0, -4, v13
	s_addc_u32 s1, s3, s1
	v_lshlrev_b32_e32 v4, 8, v8
	v_mov_b32_e32 v5, v139
	v_lshl_add_u64 v[4:5], s[0:1], 0, v[4:5]
	v_ashrrev_i32_e32 v1, 31, v0
	v_lshl_add_u64 v[4:5], v[0:1], 2, v[4:5]
	global_load_dwordx4 v[234:237], v[4:5], off
	s_waitcnt vmcnt(4)
	ds_write_b128 v245, v[222:225]
	s_waitcnt vmcnt(3)
	ds_write_b128 v245, v[210:213] offset:18432
	s_waitcnt vmcnt(1)
	ds_write_b16 v242, v230 offset:36864
	ds_write_b16_d16_hi v242, v230 offset:37136
	ds_write_b16 v242, v231 offset:37408
	ds_write_b16_d16_hi v242, v231 offset:37680
	ds_write_b16 v242, v232 offset:37952
	ds_write_b16_d16_hi v242, v232 offset:38224
	ds_write_b16 v242, v233 offset:38496
	ds_write_b16_d16_hi v242, v233 offset:38768
	ds_write_b16 v242, v226 offset:39040
	ds_write_b16_d16_hi v242, v226 offset:39312
	ds_write_b16 v242, v227 offset:39584
	ds_write_b16_d16_hi v242, v227 offset:39856
	ds_write_b16 v242, v228 offset:40128
	ds_write_b16_d16_hi v242, v228 offset:40400
	ds_write_b16 v242, v229 offset:40672
	ds_write_b16_d16_hi v243, v229 offset:36864
	s_waitcnt vmcnt(0)
	v_cvt_pk_bf16_f32 v1, v234, v139
	v_mul_lo_u32 v0, v0, s50
	v_lshlrev_b32_e32 v4, 1, v8
	v_readlane_b32 s0, v254, 57
	s_nop 1
	v_add3_u32 v0, s0, v0, v4
	ds_write_b16 v0, v1
	v_cvt_pk_bf16_f32 v1, v235, v139
	ds_write_b16 v0, v1 offset:144
	v_cvt_pk_bf16_f32 v1, v236, v139
	ds_write_b16 v0, v1 offset:288
	v_or_b32_e32 v1, 3, v13
	v_mul_lo_u32 v1, v1, s50
	v_cvt_pk_bf16_f32 v0, v237, v139
	v_add3_u32 v1, s0, v1, v4
	ds_write_b16 v1, v0
	v_mov_b32_e32 v5, v235
	v_mov_b32_e32 v6, v236
	v_mov_b32_e32 v7, v237
	v_mov_b32_e32 v9, v231
	v_mov_b32_e32 v10, v232
	v_mov_b32_e32 v11, v233
	v_mul_lo_u32 v0, v32, s50
	v_add_u32_e32 v1, 0x100, v0
	v_lshlrev_b32_e32 v0, 4, v3
	v_add_u32_e32 v3, 0x100, v0
	v_lshlrev_b32_e32 v4, 7, v32
	v_add_u32_e32 v25, v1, v0
	v_add3_u32 v1, v1, v4, v138
	v_cmp_lt_i32_e64 s[0:1], -1, v2
	v_mad_u32_u24 v3, v24, s50, v3
	s_waitcnt lgkmcnt(0)
	s_barrier
	s_and_saveexec_b64 s[4:5], s[0:1]
	s_cbranch_execz .LBB0_511
	ds_read_b128 v[4:7], v25
	ds_read_b128 v[8:11], v3 offset:18432
	v_cmp_gt_i32_e64 s[2:3], v33, v32
	s_waitcnt lgkmcnt(0)
	v_mfma_f32_16x16x32_bf16 v[4:7], v[8:11], v[4:7], 0
	v_cndmask_b32_e64 v8, 1.0, 0, s[2:3]
	v_cmp_lt_i32_e64 s[2:3], v33, v32
	s_nop 5
	v_mul_f32_e32 v4, v8, v4
	v_cndmask_b32_e64 v8, 0, 1.0, s[2:3]
	v_mul_f32_e32 v5, v8, v5
	v_or_b32_e32 v8, 2, v33
	v_cmp_gt_i32_e64 s[2:3], v8, v32
	v_cvt_pk_bf16_f32 v4, v4, v5
	s_nop 1
	v_cndmask_b32_e64 v8, 1.0, 0, s[2:3]
	v_mul_f32_e32 v6, v8, v6
	v_or_b32_e32 v8, 3, v33
	v_cmp_gt_i32_e64 s[2:3], v8, v32
	s_nop 1
	v_cndmask_b32_e64 v8, 1.0, 0, s[2:3]
	v_mul_f32_e32 v7, v8, v7
	v_cvt_pk_bf16_f32 v5, v6, v7
	ds_write_b64 v1, v[4:5] offset:58624
	ds_read_b128 v[4:7], v25
	ds_read_b128 v[8:11], v3 offset:20736
	s_waitcnt lgkmcnt(0)
	v_mfma_f32_16x16x32_bf16 v[4:7], v[8:11], v[4:7], 0
	v_or_b32_e32 v8, 16, v33
	v_cmp_gt_i32_e64 s[2:3], v8, v32
	s_nop 1
	v_cndmask_b32_e64 v8, 1.0, 0, s[2:3]
	s_nop 2
	v_mul_f32_e32 v4, v8, v4
	v_or_b32_e32 v8, 17, v33
	v_cmp_gt_i32_e64 s[2:3], v8, v32
	s_nop 1
	v_cndmask_b32_e64 v8, 1.0, 0, s[2:3]
	v_mul_f32_e32 v5, v8, v5
	v_or_b32_e32 v8, 18, v33
	v_cmp_gt_i32_e64 s[2:3], v8, v32
	v_cvt_pk_bf16_f32 v4, v4, v5
	s_nop 1
	v_cndmask_b32_e64 v8, 1.0, 0, s[2:3]
	v_mul_f32_e32 v6, v8, v6
	v_or_b32_e32 v8, 19, v33
	v_cmp_gt_i32_e64 s[2:3], v8, v32
	s_nop 1
	v_cndmask_b32_e64 v8, 1.0, 0, s[2:3]
	v_mul_f32_e32 v7, v8, v7
	v_cvt_pk_bf16_f32 v5, v6, v7
	ds_write_b64 v1, v[4:5] offset:58656

; template <int MX>
; __device__ void out_unit(const P& p, int layer, int unit, char* smem) {
;     ...
;   uint2 gpre[4];
;   {
;     const bf16* gp = p.U() + TROW(16 * w + r) * US + GC + h * 64 + 4 * q4;
; #pragma unroll
;     for (int et = 0; et < 4; ++et) gpre[et] = *(const uint2*)(gp + 16 * et);
;   }
;   __syncthreads();
;   {
;     const int t = tid >> 2;
;     if (MX == 0) {
;       const int d0 = (tid & 3) * 8;
;       *(uint4*)(Qs + t * 72 + d0) = *(const uint4*)(p.U() + TROW(t) * US + C_GQ + h * 32 + d0);
;       *(uint4*)(Ks + t * 72 + d0) = *(const uint4*)(p.U() + TROW(t) * US + C_GK + h * 32 + d0);
;     } else {
;       const int d0 = (tid & 3) * 16;
;       const bf16* qs = (MX == 1) ? (p.mlqk() + TROW(t) * 512 + h * 128 + d0) : (p.U() + TROW(t) * US + C_RQ + h * 64 + d0);
;       const bf16* ks = (MX == 1) ? (p.mlqk() + TROW(t) * 512 + h * 128 + 64 + d0) : (p.U() + TROW(t) * US + C_RK + h * 64 + d0);
;       *(uint4*)(Qs + t * 72 + d0) = *(const uint4*)qs;
;       *(uint4*)(Qs + t * 72 + d0 + 8) = *(const uint4*)(qs + 8);
;       *(uint4*)(Ks + t * 72 + d0) = *(const uint4*)ks;
;       *(uint4*)(Ks + t * 72 + d0 + 8) = *(const uint4*)(ks + 8);
;     }
;     {
;       const int e0 = (tid >> 7) * 16;
;       const int t = tid & 127;
;       constexpr int VC = (MX == 0) ? C_GV : (MX == 1 ? C_MV : C_RV);
;       const bf16* vs = p.U() + TROW(t) * US + VC + h * 64 + e0;
;       const uint4 v0 = *(const uint4*)vs, v1 = *(const uint4*)(vs + 8);
;       Vt[(e0 + 0) * 136 + t] = (bf16)(v0.x & 0xffffu); Vt[(e0 + 1) * 136 + t] = (bf16)(v0.x >> 16);
;       Vt[(e0 + 2) * 136 + t] = (bf16)(v0.y & 0xffffu); Vt[(e0 + 3) * 136 + t] = (bf16)(v0.y >> 16);
;       Vt[(e0 + 4) * 136 + t] = (bf16)(v0.z & 0xffffu); Vt[(e0 + 5) * 136 + t] = (bf16)(v0.z >> 16);
;       Vt[(e0 + 6) * 136 + t] = (bf16)(v0.w & 0xffffu); Vt[(e0 + 7) * 136 + t] = (bf16)(v0.w >> 16);
;       Vt[(e0 + 8) * 136 + t] = (bf16)(v1.x & 0xffffu); Vt[(e0 + 9) * 136 + t] = (bf16)(v1.x >> 16);
;       Vt[(e0 + 10) * 136 + t] = (bf16)(v1.y & 0xffffu); Vt[(e0 + 11) * 136 + t] = (bf16)(v1.y >> 16);
;       Vt[(e0 + 12) * 136 + t] = (bf16)(v1.z & 0xffffu); Vt[(e0 + 13) * 136 + t] = (bf16)(v1.z >> 16);
;       Vt[(e0 + 14) * 136 + t] = (bf16)(v1.w & 0xffffu); Vt[(e0 + 15) * 136 + t] = (bf16)(v1.w >> 16);
;     }
;     if (MX == 0) {
;       const int d = tid & 31, e0 = (tid >> 5) * 4;
.LBB0_579:
	s_lshr_b32 s9, s9, 20
	s_lshl_b32 s12, s12, 7
	s_mul_i32 s13, s9, 0x2010
	s_and_b32 s12, s12, 0xff80
	s_add_i32 s12, s12, s13
	s_addk_i32 s12, 0xff90
	s_and_saveexec_b64 s[14:15], s[4:5]
	s_xor_b64 s[4:5], exec, s[14:15]
	v_or_b32_e32 v2, s12, v31
	v_add_u32_e32 v3, v2, v1
	s_andn2_b64 s[0:1], s[0:1], exec
	s_or_b64 exec, exec, s[4:5]
	s_mul_i32 s13, s9, 0x70
	s_addk_i32 s13, 0x4020
	s_and_saveexec_b64 s[4:5], s[0:1]
	v_add_u32_e32 v3, s13, v30
	s_or_b64 exec, exec, s[4:5]
	s_and_b32 s14, s7, 3
	s_add_u32 s0, s76, s8
	s_addc_u32 s1, s77, 0
	v_mov_b64_e32 v[6:7], s[0:1]
	v_bfe_u32 v2, v0, 4, 2
	v_mad_i64_i32 v[6:7], s[0:1], v3, s54, v[6:7]
	s_lshl_b32 s96, s14, 7
	v_lshl_add_u64 v[6:7], v[6:7], 0, s[96:97]
	v_lshlrev_b32_e32 v138, 3, v2
	v_lshl_add_u64 v[6:7], v[6:7], 0, v[138:139]
	s_mov_b64 s[0:1], 0x1230
	s_movk_i32 s8, 0x1000
	v_lshl_add_u64 v[8:9], v[6:7], 0, s[0:1]
	v_add_co_u32_e32 v6, vcc, s8, v6
	s_mov_b32 s0, 0x17683000
	s_nop 0
	v_addc_co_u32_e32 v7, vcc, 0, v7, vcc
	global_load_dwordx2 v[26:27], v[6:7], off offset:560
	global_load_dwordx2 v[24:25], v[8:9], off offset:32
	global_load_dwordx2 v[22:23], v[8:9], off offset:64
	global_load_dwordx2 v[20:21], v[8:9], off offset:96
	s_barrier
	v_ashrrev_i32_e32 v3, 2, v0
	s_movk_i32 s7, 0x70
	s_add_u32 s0, s76, s0
	v_cmp_gt_i32_e32 vcc, s7, v3
	s_addc_u32 s1, s77, 0
	s_and_b64 vcc, s[2:3], vcc
	v_mov_b32_e32 v5, s12
	v_mov_b32_e32 v16, s13
	v_cndmask_b32_e32 v6, v5, v16, vcc
	v_add_u32_e32 v6, v6, v3
	v_ashrrev_i32_e32 v7, 31, v6
	v_lshlrev_b64 v[6:7], 10, v[6:7]
	s_mov_b32 s4, 0x17683000
	v_lshl_add_u64 v[8:9], s[0:1], 0, v[6:7]
	s_lshl_b32 s0, s14, 8
	s_add_u32 s4, s76, s4
	s_mov_b32 s1, s97
	v_lshlrev_b32_e32 v10, 5, v0
	s_addc_u32 s5, s77, 0
	v_lshl_add_u64 v[8:9], v[8:9], 0, s[0:1]
	v_and_b32_e32 v10, 0x60, v10
	v_mov_b32_e32 v11, v139
	v_lshl_add_u64 v[6:7], s[4:5], 0, v[6:7]
	v_lshl_add_u64 v[12:13], v[8:9], 0, v[10:11]
	v_lshl_add_u64 v[6:7], v[6:7], 0, s[0:1]
	v_lshl_add_u64 v[14:15], v[6:7], 0, v[10:11]
	global_load_dwordx4 v[222:225], v[12:13], off
	v_mul_lo_u32 v3, v3, s50
	v_add3_u32 v245, s45, v3, v10
	s_mov_b32 s0, 0x6180000
	v_and_b32_e32 v17, 0x7f, v0
	v_cmp_gt_u32_e32 vcc, s7, v17
	s_mov_b32 s7, s97
	v_and_b32_e32 v1, 63, v0
	s_movk_i32 s44, 0x70
	s_movk_i32 s10, 0x1000
	s_movk_i32 s15, 0x110
	global_load_dwordx4 v[210:213], v[12:13], off offset:16
	global_load_dwordx4 v[214:217], v[14:15], off offset:128
	global_load_dwordx4 v[218:221], v[14:15], off offset:144
	s_add_u32 s0, s76, s0
	s_addc_u32 s1, s77, 0
	s_and_b64 vcc, s[2:3], vcc
	v_cndmask_b32_e32 v5, v5, v16, vcc
	v_ashrrev_i32_e32 v3, 3, v0
	v_add_u32_e32 v5, v5, v17
	v_mov_b64_e32 v[6:7], s[0:1]
	v_and_b32_e32 v14, -16, v3
	v_mad_i64_i32 v[6:7], s[0:1], v5, s54, v[6:7]
	v_lshl_add_u64 v[6:7], v[6:7], 0, s[96:97]
	v_ashrrev_i32_e32 v15, 31, v14
	v_lshl_add_u64 v[6:7], v[14:15], 1, v[6:7]
	s_mov_b64 s[0:1], 0x1020
	v_lshl_add_u64 v[10:11], v[6:7], 0, s[0:1]
	v_add_co_u32_e32 v6, vcc, s8, v6
	s_movk_i32 s0, 0x110
	s_nop 0
	v_addc_co_u32_e32 v7, vcc, 0, v7, vcc
	global_load_dwordx4 v[226:229], v[6:7], off offset:32
	s_nop 0
	global_load_dwordx4 v[230:233], v[10:11], off offset:16
	v_or_b32_e32 v3, 15, v3
	v_mul_lo_u32 v5, v14, s0
	v_lshlrev_b32_e32 v14, 1, v17
	v_mul_lo_u32 v3, v3, s0
	v_add3_u32 v242, s45, v5, v14
	v_add3_u32 v243, s45, v3, v14
	s_mov_b32 s0, 0x1aee3400
	s_add_u32 s4, s76, s0
	s_addc_u32 s5, s77, 0
	s_lshl_b64 s[0:1], s[6:7], 6
	v_or_b32_e32 v8, s0, v1
	v_mov_b32_e32 v9, s1
	v_lshlrev_b32_e32 v6, 3, v4
	v_lshlrev_b64 v[8:9], 8, v[8:9]
	v_lshl_add_u64 v[8:9], s[4:5], 0, v[8:9]
	v_ashrrev_i32_e32 v7, 31, v6
	v_lshl_add_u64 v[10:11], v[6:7], 2, v[8:9]
	global_load_dwordx4 v[234:237], v[10:11], off offset:16
	s_nop 0
	global_load_dwordx4 v[238:241], v[10:11], off
	s_movk_i32 s4, 0x480
	v_mul_lo_u32 v5, v4, s4
	v_lshlrev_b32_e32 v1, 1, v1
	v_readlane_b32 s4, v254, 57
	s_waitcnt vmcnt(7)
	ds_write_b128 v245, v[222:225]
	s_waitcnt vmcnt(6)
	ds_write_b128 v245, v[210:213] offset:16
	s_waitcnt vmcnt(5)
	ds_write_b128 v245, v[214:217] offset:18432
	s_waitcnt vmcnt(4)
	ds_write_b128 v245, v[218:221] offset:18448
	s_waitcnt vmcnt(3)
	ds_write_b16 v242, v226 offset:36864
	ds_write_b16_d16_hi v242, v226 offset:37136
	ds_write_b16 v242, v227 offset:37408
	ds_write_b16_d16_hi v242, v227 offset:37680
	ds_write_b16 v242, v228 offset:37952
	ds_write_b16_d16_hi v242, v228 offset:38224
	ds_write_b16 v242, v229 offset:38496
	ds_write_b16_d16_hi v242, v229 offset:38768
	s_waitcnt vmcnt(2)
	ds_write_b16 v242, v230 offset:39040
	ds_write_b16_d16_hi v242, v230 offset:39312
	ds_write_b16 v242, v231 offset:39584
	ds_write_b16_d16_hi v242, v231 offset:39856
	ds_write_b16 v242, v232 offset:40128
	ds_write_b16_d16_hi v242, v232 offset:40400
	ds_write_b16 v242, v233 offset:40672
	ds_write_b16_d16_hi v243, v233 offset:36864
	s_waitcnt vmcnt(0)
	v_cvt_pk_bf16_f32 v3, v238, v139
	s_nop 0
	v_add3_u32 v1, s4, v5, v1
	ds_write_b16 v1, v3
	v_cvt_pk_bf16_f32 v3, v239, v139
	ds_write_b16 v1, v3 offset:144
	v_cvt_pk_bf16_f32 v3, v240, v139
	ds_write_b16 v1, v3 offset:288
	v_cvt_pk_bf16_f32 v3, v241, v139
	ds_write_b16 v1, v3 offset:432
	v_cvt_pk_bf16_f32 v3, v234, v139
	ds_write_b16 v1, v3 offset:576
	v_cvt_pk_bf16_f32 v3, v235, v139
	ds_write_b16 v1, v3 offset:720
	v_cvt_pk_bf16_f32 v3, v236, v139
	s_mov_b32 s4, 0x1b724e00
	ds_write_b16 v1, v3 offset:864
	v_cvt_pk_bf16_f32 v3, v237, v139
	ds_write_b16 v1, v3 offset:1008
	v_mov_b32_e32 v6, v234
	v_mov_b32_e32 v7, v235
	v_mov_b32_e32 v8, v236
	v_mov_b32_e32 v9, v237
	v_mov_b32_e32 v10, v238
	v_mov_b32_e32 v11, v239
	v_mov_b32_e32 v12, v240
	v_mov_b32_e32 v13, v241
	s_add_u32 s8, s76, s4
	s_addc_u32 s9, s77, 0
	s_lshl_b64 s[4:5], s[6:7], 2
	s_add_u32 s4, s8, s4
	s_addc_u32 s5, s9, s5
	global_load_dword v32, v139, s[4:5]
	s_movk_i32 s4, 0x80
	v_cmp_gt_i32_e32 vcc, s4, v0
	s_and_saveexec_b64 s[4:5], vcc
	s_cbranch_execz .LBB0_585
;   __device__ __forceinline__ bf16* h() const { unsigned o_ = (unsigned)(OFF_h); asm volatile("" : "+s"(o_)); return (bf16*)(ws + o_); }
;   __device__ __forceinline__ float* ml_n() const { unsigned o_ = (unsigned)(OFF_ml_n); asm volatile("" : "+s"(o_)); return (float*)(ws + o_); }
;   __device__ __forceinline__ float* ml_mprev() const { unsigned o_ = (unsigned)(OFF_ml_mprev); asm volatile("" : "+s"(o_)); return (float*)(ws + o_); }
;   __device__ __forceinline__ float* ml_g() const { unsigned o_ = (unsigned)(OFF_ml_g); asm volatile("" : "+s"(o_)); return (float*)(ws + o_); }
;   __device__ __forceinline__ float* ml_pm() const { unsigned o_ = (unsigned)(OFF_ml_pm); asm volatile("" : "+s"(o_)); return (float*)(ws + o_); }
;   __device__ __forceinline__ float* ml_cf() const { unsigned o_ = (unsigned)(OFF_ml_cf); asm volatile("" : "+s"(o_)); return (float*)(ws + o_); }
; __device__ __forceinline__ bf16 f2bf(float f) { return (bf16)(pk2(f, 0.f) & 0xffffu); }
; template <int MX>
; __device__ void out_unit(const P& p, int layer, int unit, char* smem) {
;     ...
;     if (MX == 1) {
;       mprev = p.ml_mprev()[unit];
;       if (tid < 128) {
;         const float g = p.ml_g()[TROW(tid) * 4 + h], pm = p.ml_pm()[TROW(tid) * 4 + h], cf = p.ml_cf()[TROW(tid) * 4 + h];
;         va[tid] = fmaxf(mprev, pm); vb[tid] = g; vc[tid] = cf;
;         Vt[64 * 136 + tid] = (bf16)0x3F80;
; #pragma unroll
;         for (int i = 65; i < 80; ++i) Vt[i * 136 + tid] = 0;
;       }
;       if (tid < 64) {
;         St[64 * 72 + tid] = f2bf(p.ml_n()[(size_t)unit * 64 + tid]);
; #pragma unroll
;         for (int i = 65; i < 80; ++i) St[i * 72 + tid] = 0;
;       }
	s_mov_b32 s7, 0x1b725700
	s_add_u32 s8, s76, s7
	v_cmp_gt_i32_e32 vcc, s44, v0
	s_addc_u32 s9, s77, 0
	s_and_b64 vcc, s[2:3], vcc
	v_mov_b32_e32 v1, s12
	v_mov_b32_e32 v3, s13
	v_cndmask_b32_e32 v1, v1, v3, vcc
	v_add_u32_e32 v6, v1, v0
	v_ashrrev_i32_e32 v7, 31, v6
	v_lshlrev_b64 v[6:7], 4, v[6:7]
	v_lshl_add_u64 v[8:9], s[8:9], 0, v[6:7]
	s_lshl_b32 s96, s14, 2
	v_lshl_add_u64 v[8:9], v[8:9], 0, s[96:97]
	s_mov_b32 s7, 0x1b766700
	global_load_dword v1, v[8:9], off
	s_add_u32 s8, s76, s7
	s_addc_u32 s9, s77, 0
	v_lshl_add_u64 v[8:9], s[8:9], 0, v[6:7]
	v_lshl_add_u64 v[8:9], v[8:9], 0, s[96:97]
	global_load_dword v3, v[8:9], off
	s_mov_b32 s7, 0x1b7a7700
	s_add_u32 s8, s76, s7
	s_addc_u32 s9, s77, 0
	v_lshl_add_u64 v[6:7], s[8:9], 0, v[6:7]
	v_lshl_add_u64 v[6:7], v[6:7], 0, s[96:97]
	global_load_dword v5, v[6:7], off
	s_waitcnt vmcnt(3)
	v_max_f32_e32 v6, v32, v32
	s_waitcnt vmcnt(1)
	v_max_f32_e32 v3, v3, v3
	v_max_f32_e32 v3, v6, v3
	v_lshl_add_u32 v6, v0, 2, v196
	v_add_u32_e32 v7, 0x19a00, v6
	ds_write_b32 v7, v3
	v_add_u32_e32 v3, 0x19c00, v6
	ds_write_b32 v3, v1
	v_add_u32_e32 v1, 0x19e00, v6
	s_waitcnt vmcnt(0)
	ds_write_b32 v1, v5
	v_lshl_add_u32 v1, v0, 1, v196
	ds_write_b16 v1, v192 offset:54272
	ds_write_b16 v1, v139 offset:54544
	ds_write_b16 v1, v139 offset:54816
	ds_write_b16 v1, v139 offset:55088
	ds_write_b16 v1, v139 offset:55360
	ds_write_b16 v1, v139 offset:55632
	ds_write_b16 v1, v139 offset:55904
	ds_write_b16 v1, v139 offset:56176
	ds_write_b16 v1, v139 offset:56448
	ds_write_b16 v1, v139 offset:56720
	ds_write_b16 v1, v139 offset:56992
	ds_write_b16 v1, v139 offset:57264
	ds_write_b16 v1, v139 offset:57536
	ds_write_b16 v1, v139 offset:57808
	ds_write_b16 v1, v139 offset:58080
	ds_write_b16 v1, v139 offset:58352

;   __device__ __forceinline__ bf16* h() const { unsigned o_ = (unsigned)(OFF_h); asm volatile("" : "+s"(o_)); return (bf16*)(ws + o_); }
;   __device__ __forceinline__ bf16* y() const { unsigned o_ = (unsigned)(OFF_y); asm volatile("" : "+s"(o_)); return (bf16*)(ws + o_); }
; __device__ __forceinline__ unsigned pk2(float a, float b) { unsigned r; asm("v_cvt_pk_bf16_f32 %0, %1, %2" : "=v"(r) : "v"(a), "v"(b)); return r; }
; __device__ __forceinline__ float lo16(unsigned v) { return __uint_as_float(v << 16); }
; __device__ __forceinline__ float hi16(unsigned v) { return __uint_as_float(v & 0xffff0000u); }
;   __device__ __forceinline__ void fused(f32x4 (&acc)[2][2][4][2], const pg8::Unit& u, int wr, int wc, int fr, int fq, PG8_LAS unsigned char* lds, int wid,
;                                         int lane) const {
;     ...
;     const int colb = u.pn * 256 + wc * 32 + 8 * fq;
; #pragma unroll
;     for (int bj = 0; bj < 2; ++bj) {
;       const int c = colb + bj * 128;
;       const f32x4 gp0 = *(const f32x4*)(gpost + c), gp1 = *(const f32x4*)(gpost + c + 4);
; #pragma unroll
;       for (int ai = 0; ai < 2; ++ai)
; #pragma unroll
;         for (int m = 0; m < 4; ++m) {
;           const int rl = ai * 128 + wr * 64 + m * 16 + fr;
;           int r = u.pm * 256 + rl;
;           asm volatile("" : "+v"(r));
;           const float rs = rsv[rl];
;           const uint4 hb_ = *(const uint4*)(h + (size_t)r * D + c);
;           const f32x4 hv0 = f32x4{lo16(hb_.x), hi16(hb_.x), lo16(hb_.y), hi16(hb_.y)};
;           const f32x4 hv1 = f32x4{lo16(hb_.z), hi16(hb_.z), lo16(hb_.w), hi16(hb_.w)};
;           const f32x4 nv0 = hv0 + acc[ai][bj][m][0] * rs * gp0;
;           const f32x4 nv1 = hv1 + acc[ai][bj][m][1] * rs * gp1;
;           acc[ai][bj][m][0] = nv0; acc[ai][bj][m][1] = nv1;
;           if (!LAST) {
;             uint4 ho_; ho_.x = pk2(nv0[0], nv0[1]); ho_.y = pk2(nv0[2], nv0[3]); ho_.z = pk2(nv1[0], nv1[1]); ho_.w = pk2(nv1[2], nv1[3]);
;             *(uint4*)(h + (size_t)r * D + c) = ho_;
.LBB0_841:
	s_or_b64 exec, exec, s[0:1]
	s_add_u32 s0, s76, s35
	s_addc_u32 s1, s77, 0
	s_lshl_b32 s12, s36, 5
	s_lshl_b32 s13, s34, 8
	v_lshrrev_b32_e32 v128, 1, v156
	s_or_b32 s12, s13, s12
	v_and_or_b32 v168, v128, 24, s12
	v_lshl_add_u32 v152, s16, 8, v157
	v_ashrrev_i32_e32 v169, 31, v168
	v_lshl_add_u64 v[186:187], v[168:169], 2, s[8:9]
	v_mov_b32_e32 v148, v152
	s_waitcnt lgkmcnt(0)
	s_barrier
	global_load_dwordx4 v[128:131], v[186:187], off offset:16
	global_load_dwordx4 v[132:135], v[186:187], off
	v_lshl_add_u32 v138, v157, 2, v196
	v_ashrrev_i32_e32 v149, 31, v148
	v_lshlrev_b64 v[148:149], 11, v[148:149]
	v_lshl_add_u64 v[158:159], s[0:1], 0, v[148:149]
	v_lshlrev_b64 v[148:149], 1, v[168:169]
	v_lshl_add_u64 v[162:163], v[158:159], 0, v[148:149]
	v_mov_b32_e32 v244, v152
	v_ashrrev_i32_e32 v245, 31, v244
	v_lshlrev_b64 v[244:245], 11, v[244:245]
	v_lshl_add_u64 v[244:245], s[0:1], 0, v[244:245]
	v_lshl_add_u64 v[244:245], v[244:245], 0, v[148:149]
	global_load_dwordx4 v[212:215], v[244:245], off
	v_add_u32_e32 v244, 0x10, v152
	v_ashrrev_i32_e32 v245, 31, v244
	v_lshlrev_b64 v[244:245], 11, v[244:245]
	v_lshl_add_u64 v[244:245], s[0:1], 0, v[244:245]
	v_lshl_add_u64 v[244:245], v[244:245], 0, v[148:149]
	global_load_dwordx4 v[216:219], v[244:245], off
	v_add_u32_e32 v244, 0x20, v152
	v_ashrrev_i32_e32 v245, 31, v244
	v_lshlrev_b64 v[244:245], 11, v[244:245]
	v_lshl_add_u64 v[244:245], s[0:1], 0, v[244:245]
	v_lshl_add_u64 v[244:245], v[244:245], 0, v[148:149]
	global_load_dwordx4 v[220:223], v[244:245], off
	v_add_u32_e32 v244, 0x30, v152
	v_ashrrev_i32_e32 v245, 31, v244
	v_lshlrev_b64 v[244:245], 11, v[244:245]
	v_lshl_add_u64 v[244:245], s[0:1], 0, v[244:245]
	v_lshl_add_u64 v[244:245], v[244:245], 0, v[148:149]
	global_load_dwordx4 v[224:227], v[244:245], off
	v_add_u32_e32 v244, 0x80, v152
	v_ashrrev_i32_e32 v245, 31, v244
	v_lshlrev_b64 v[244:245], 11, v[244:245]
	v_lshl_add_u64 v[244:245], s[0:1], 0, v[244:245]
	v_lshl_add_u64 v[244:245], v[244:245], 0, v[148:149]
	global_load_dwordx4 v[228:231], v[244:245], off
	v_add_u32_e32 v244, 0x90, v152
	v_ashrrev_i32_e32 v245, 31, v244
	v_lshlrev_b64 v[244:245], 11, v[244:245]
	v_lshl_add_u64 v[244:245], s[0:1], 0, v[244:245]
	v_lshl_add_u64 v[244:245], v[244:245], 0, v[148:149]
	global_load_dwordx4 v[232:235], v[244:245], off
	v_add_u32_e32 v244, 0xa0, v152
	v_ashrrev_i32_e32 v245, 31, v244
	v_lshlrev_b64 v[244:245], 11, v[244:245]
	v_lshl_add_u64 v[244:245], s[0:1], 0, v[244:245]
	v_lshl_add_u64 v[244:245], v[244:245], 0, v[148:149]
	global_load_dwordx4 v[236:239], v[244:245], off
	v_add_u32_e32 v244, 0xb0, v152
	v_ashrrev_i32_e32 v245, 31, v244
	v_lshlrev_b64 v[244:245], 11, v[244:245]
	v_lshl_add_u64 v[244:245], s[0:1], 0, v[244:245]
	v_lshl_add_u64 v[244:245], v[244:245], 0, v[148:149]
	global_load_dwordx4 v[240:243], v[244:245], off
	ds_read_b32 v156, v138 offset:4096
	v_add_u32_e32 v150, 16, v152
	v_mov_b32_e32 v164, v150
	s_waitcnt lgkmcnt(0)
	v_pk_mul_f32 v[124:125], v[124:125], v[156:157] op_sel_hi:[1,0]
	v_pk_mul_f32 v[126:127], v[126:127], v[156:157] op_sel_hi:[1,0]
	v_pk_mul_f32 v[120:121], v[120:121], v[156:157] op_sel_hi:[1,0]
	v_pk_mul_f32 v[122:123], v[122:123], v[156:157] op_sel_hi:[1,0]
	s_waitcnt vmcnt(0)
	v_lshlrev_b32_e32 v156, 16, v212
	v_and_b32_e32 v157, 0xffff0000, v212
	v_lshlrev_b32_e32 v158, 16, v213
	v_and_b32_e32 v159, 0xffff0000, v213
	v_lshlrev_b32_e32 v166, 16, v214
	v_and_b32_e32 v167, 0xffff0000, v214
	v_lshlrev_b32_e32 v160, 16, v215
	v_and_b32_e32 v161, 0xffff0000, v215
	v_pk_fma_f32 v[182:183], v[134:135], v[126:127], v[158:159]
	v_pk_fma_f32 v[184:185], v[132:133], v[124:125], v[156:157]
	v_pk_fma_f32 v[178:179], v[130:131], v[122:123], v[160:161]
	v_pk_fma_f32 v[180:181], v[128:129], v[120:121], v[166:167]
	v_cvt_pk_bf16_f32 v120, v184, v185
	v_cvt_pk_bf16_f32 v121, v182, v183
	v_cvt_pk_bf16_f32 v123, v178, v179
	s_nop 0
	v_cvt_pk_bf16_f32 v122, v180, v181
	global_store_dwordx4 v[162:163], v[120:123], off
	ds_read_b32 v156, v138 offset:4160
	v_ashrrev_i32_e32 v165, 31, v164
	v_lshlrev_b64 v[120:121], 11, v[164:165]
	v_lshl_add_u64 v[120:121], s[0:1], 0, v[120:121]
	v_lshl_add_u64 v[126:127], v[120:121], 0, v[148:149]
	v_add_u32_e32 v120, 32, v152
	v_mov_b32_e32 v158, v120
	s_waitcnt lgkmcnt(0)
	v_pk_mul_f32 v[116:117], v[116:117], v[156:157] op_sel_hi:[1,0]
	v_pk_mul_f32 v[118:119], v[118:119], v[156:157] op_sel_hi:[1,0]
	v_pk_mul_f32 v[112:113], v[112:113], v[156:157] op_sel_hi:[1,0]
	v_pk_mul_f32 v[114:115], v[114:115], v[156:157] op_sel_hi:[1,0]
	v_lshlrev_b32_e32 v156, 16, v216
	v_and_b32_e32 v157, 0xffff0000, v216
	v_lshlrev_b32_e32 v122, 16, v217
	v_and_b32_e32 v123, 0xffff0000, v217
	v_lshlrev_b32_e32 v160, 16, v218
	v_and_b32_e32 v161, 0xffff0000, v218
	v_lshlrev_b32_e32 v124, 16, v219
	v_and_b32_e32 v125, 0xffff0000, v219
	v_pk_fma_f32 v[174:175], v[134:135], v[118:119], v[122:123]
	v_pk_fma_f32 v[176:177], v[132:133], v[116:117], v[156:157]
	v_pk_fma_f32 v[170:171], v[130:131], v[114:115], v[124:125]
	v_pk_fma_f32 v[172:173], v[128:129], v[112:113], v[160:161]
	v_cvt_pk_bf16_f32 v112, v176, v177
	v_cvt_pk_bf16_f32 v113, v174, v175
	v_cvt_pk_bf16_f32 v115, v170, v171
	s_nop 0
	v_cvt_pk_bf16_f32 v114, v172, v173
	global_store_dwordx4 v[126:127], v[112:115], off
	ds_read_b32 v122, v138 offset:4224
	v_ashrrev_i32_e32 v159, 31, v158
	v_lshlrev_b64 v[112:113], 11, v[158:159]
	v_lshl_add_u64 v[112:113], s[0:1], 0, v[112:113]
	v_lshl_add_u64 v[118:119], v[112:113], 0, v[148:149]
	v_add_u32_e32 v112, 48, v152
	v_mov_b32_e32 v124, v112
	s_waitcnt lgkmcnt(0)
;   __device__ __forceinline__ bf16* h() const { unsigned o_ = (unsigned)(OFF_h); asm volatile("" : "+s"(o_)); return (bf16*)(ws + o_); }
;   __device__ __forceinline__ bf16* y() const { unsigned o_ = (unsigned)(OFF_y); asm volatile("" : "+s"(o_)); return (bf16*)(ws + o_); }
; __device__ __forceinline__ unsigned pk2(float a, float b) { unsigned r; asm("v_cvt_pk_bf16_f32 %0, %1, %2" : "=v"(r) : "v"(a), "v"(b)); return r; }
; __device__ __forceinline__ float lo16(unsigned v) { return __uint_as_float(v << 16); }
; __device__ __forceinline__ float hi16(unsigned v) { return __uint_as_float(v & 0xffff0000u); }
;   __device__ __forceinline__ void fused(f32x4 (&acc)[2][2][4][2], const pg8::Unit& u, int wr, int wc, int fr, int fq, PG8_LAS unsigned char* lds, int wid,
;                                         int lane) const {
;     ...
;       for (int ai = 0; ai < 2; ++ai)
; #pragma unroll
;         for (int m = 0; m < 4; ++m) {
;           const int rl = ai * 128 + wr * 64 + m * 16 + fr;
;           int r = u.pm * 256 + rl;
;           asm volatile("" : "+v"(r));
;           const float rs = rsv[rl];
;           const uint4 hb_ = *(const uint4*)(h + (size_t)r * D + c);
;           const f32x4 hv0 = f32x4{lo16(hb_.x), hi16(hb_.x), lo16(hb_.y), hi16(hb_.y)};
;           const f32x4 hv1 = f32x4{lo16(hb_.z), hi16(hb_.z), lo16(hb_.w), hi16(hb_.w)};
;           const f32x4 nv0 = hv0 + acc[ai][bj][m][0] * rs * gp0;
;           const f32x4 nv1 = hv1 + acc[ai][bj][m][1] * rs * gp1;
;           acc[ai][bj][m][0] = nv0; acc[ai][bj][m][1] = nv1;
;           if (!LAST) {
;             uint4 ho_; ho_.x = pk2(nv0[0], nv0[1]); ho_.y = pk2(nv0[2], nv0[3]); ho_.z = pk2(nv1[0], nv1[1]); ho_.w = pk2(nv1[2], nv1[3]);
;             *(uint4*)(h + (size_t)r * D + c) = ho_;
	v_pk_mul_f32 v[108:109], v[108:109], v[122:123] op_sel_hi:[1,0]
	v_pk_mul_f32 v[110:111], v[110:111], v[122:123] op_sel_hi:[1,0]
	v_pk_mul_f32 v[104:105], v[104:105], v[122:123] op_sel_hi:[1,0]
	v_pk_mul_f32 v[106:107], v[106:107], v[122:123] op_sel_hi:[1,0]
	v_lshlrev_b32_e32 v122, 16, v220
	v_and_b32_e32 v123, 0xffff0000, v220
	v_lshlrev_b32_e32 v114, 16, v221
	v_and_b32_e32 v115, 0xffff0000, v221
	v_lshlrev_b32_e32 v126, 16, v222
	v_and_b32_e32 v127, 0xffff0000, v222
	v_lshlrev_b32_e32 v116, 16, v223
	v_and_b32_e32 v117, 0xffff0000, v223
	v_pk_fma_f32 v[164:165], v[134:135], v[110:111], v[114:115]
	v_pk_fma_f32 v[166:167], v[132:133], v[108:109], v[122:123]
	v_pk_fma_f32 v[160:161], v[130:131], v[106:107], v[116:117]
	v_pk_fma_f32 v[162:163], v[128:129], v[104:105], v[126:127]
	v_cvt_pk_bf16_f32 v104, v166, v167
	v_cvt_pk_bf16_f32 v105, v164, v165
	v_cvt_pk_bf16_f32 v107, v160, v161
	s_nop 0
	v_cvt_pk_bf16_f32 v106, v162, v163
	global_store_dwordx4 v[118:119], v[104:107], off
	ds_read_b32 v114, v138 offset:4288
	v_ashrrev_i32_e32 v125, 31, v124
	v_lshlrev_b64 v[104:105], 11, v[124:125]
	v_lshl_add_u64 v[104:105], s[0:1], 0, v[104:105]
	v_lshl_add_u64 v[110:111], v[104:105], 0, v[148:149]
	v_add_u32_e32 v104, 0x80, v152
	v_mov_b32_e32 v116, v104
	s_waitcnt lgkmcnt(0)
	v_pk_mul_f32 v[100:101], v[100:101], v[114:115] op_sel_hi:[1,0]
	v_pk_mul_f32 v[102:103], v[102:103], v[114:115] op_sel_hi:[1,0]
	v_pk_mul_f32 v[96:97], v[96:97], v[114:115] op_sel_hi:[1,0]
	v_pk_mul_f32 v[98:99], v[98:99], v[114:115] op_sel_hi:[1,0]
	v_lshlrev_b32_e32 v114, 16, v224
	v_and_b32_e32 v115, 0xffff0000, v224
	v_lshlrev_b32_e32 v106, 16, v225
	v_and_b32_e32 v107, 0xffff0000, v225
	v_lshlrev_b32_e32 v118, 16, v226
	v_and_b32_e32 v119, 0xffff0000, v226
	v_lshlrev_b32_e32 v108, 16, v227
	v_and_b32_e32 v109, 0xffff0000, v227
	v_pk_fma_f32 v[156:157], v[134:135], v[102:103], v[106:107]
	v_pk_fma_f32 v[158:159], v[132:133], v[100:101], v[114:115]
	v_pk_fma_f32 v[124:125], v[130:131], v[98:99], v[108:109]
	v_pk_fma_f32 v[126:127], v[128:129], v[96:97], v[118:119]
	v_cvt_pk_bf16_f32 v96, v158, v159
	v_cvt_pk_bf16_f32 v97, v156, v157
	v_cvt_pk_bf16_f32 v99, v124, v125
	s_nop 0
	v_cvt_pk_bf16_f32 v98, v126, v127
	global_store_dwordx4 v[110:111], v[96:99], off
	ds_read_b32 v106, v138 offset:4608
	v_ashrrev_i32_e32 v117, 31, v116
	v_lshlrev_b64 v[96:97], 11, v[116:117]
	v_lshl_add_u64 v[96:97], s[0:1], 0, v[96:97]
	v_lshl_add_u64 v[102:103], v[96:97], 0, v[148:149]
	v_add_u32_e32 v96, 0x90, v152
	v_mov_b32_e32 v108, v96
	s_waitcnt lgkmcnt(0)
	v_pk_mul_f32 v[92:93], v[92:93], v[106:107] op_sel_hi:[1,0]
	v_pk_mul_f32 v[94:95], v[94:95], v[106:107] op_sel_hi:[1,0]
	v_pk_mul_f32 v[88:89], v[88:89], v[106:107] op_sel_hi:[1,0]
	v_pk_mul_f32 v[90:91], v[90:91], v[106:107] op_sel_hi:[1,0]
	v_lshlrev_b32_e32 v106, 16, v228
	v_and_b32_e32 v107, 0xffff0000, v228
	v_lshlrev_b32_e32 v98, 16, v229
	v_and_b32_e32 v99, 0xffff0000, v229
	v_lshlrev_b32_e32 v110, 16, v230
	v_and_b32_e32 v111, 0xffff0000, v230
	v_lshlrev_b32_e32 v100, 16, v231
	v_and_b32_e32 v101, 0xffff0000, v231
	v_pk_fma_f32 v[118:119], v[134:135], v[94:95], v[98:99]
	v_pk_fma_f32 v[122:123], v[132:133], v[92:93], v[106:107]
	v_pk_fma_f32 v[114:115], v[130:131], v[90:91], v[100:101]
	v_pk_fma_f32 v[116:117], v[128:129], v[88:89], v[110:111]
	v_cvt_pk_bf16_f32 v88, v122, v123
	v_cvt_pk_bf16_f32 v89, v118, v119
	v_cvt_pk_bf16_f32 v91, v114, v115
	s_nop 0
	v_cvt_pk_bf16_f32 v90, v116, v117
	global_store_dwordx4 v[102:103], v[88:91], off
	ds_read_b32 v94, v138 offset:4672
	v_ashrrev_i32_e32 v109, 31, v108
	v_lshlrev_b64 v[88:89], 11, v[108:109]
	v_lshl_add_u64 v[88:89], s[0:1], 0, v[88:89]
	v_lshl_add_u64 v[98:99], v[88:89], 0, v[148:149]
	v_add_u32_e32 v88, 0xa0, v152
	v_mov_b32_e32 v100, v88
	s_waitcnt lgkmcnt(0)
	v_pk_mul_f32 v[84:85], v[84:85], v[94:95] op_sel_hi:[1,0]
	v_pk_mul_f32 v[86:87], v[86:87], v[94:95] op_sel_hi:[1,0]
	v_pk_mul_f32 v[80:81], v[80:81], v[94:95] op_sel_hi:[1,0]
	v_pk_mul_f32 v[82:83], v[82:83], v[94:95] op_sel_hi:[1,0]
	v_lshlrev_b32_e32 v94, 16, v232
	v_and_b32_e32 v95, 0xffff0000, v232
	v_lshlrev_b32_e32 v90, 16, v233
	v_and_b32_e32 v91, 0xffff0000, v233
	v_lshlrev_b32_e32 v102, 16, v234
	v_and_b32_e32 v103, 0xffff0000, v234
	v_lshlrev_b32_e32 v92, 16, v235
	v_and_b32_e32 v93, 0xffff0000, v235
	v_pk_fma_f32 v[86:87], v[134:135], v[86:87], v[90:91]
	v_pk_fma_f32 v[90:91], v[132:133], v[84:85], v[94:95]
	v_pk_fma_f32 v[82:83], v[130:131], v[82:83], v[92:93]
	v_pk_fma_f32 v[84:85], v[128:129], v[80:81], v[102:103]
	v_cvt_pk_bf16_f32 v92, v90, v91
	v_cvt_pk_bf16_f32 v93, v86, v87
	v_cvt_pk_bf16_f32 v95, v82, v83
	s_nop 0
	v_cvt_pk_bf16_f32 v94, v84, v85
	global_store_dwordx4 v[98:99], v[92:95], off
	s_nop 0
	v_ashrrev_i32_e32 v101, 31, v100
	v_lshlrev_b64 v[80:81], 11, v[100:101]
	v_lshl_add_u64 v[80:81], s[0:1], 0, v[80:81]
	v_lshl_add_u64 v[98:99], v[80:81], 0, v[148:149]
	ds_read_b32 v100, v138 offset:4736
	v_add_u32_e32 v80, 0xb0, v152
	v_mov_b32_e32 v102, v80
	s_waitcnt lgkmcnt(0)
	v_pk_mul_f32 v[106:107], v[76:77], v[100:101] op_sel_hi:[1,0]
	v_pk_mul_f32 v[76:77], v[78:79], v[100:101] op_sel_hi:[1,0]
	v_pk_mul_f32 v[108:109], v[72:73], v[100:101] op_sel_hi:[1,0]
	v_pk_mul_f32 v[72:73], v[74:75], v[100:101] op_sel_hi:[1,0]
	v_lshlrev_b32_e32 v74, 16, v236
	v_and_b32_e32 v75, 0xffff0000, v236
	v_lshlrev_b32_e32 v78, 16, v237
	v_and_b32_e32 v79, 0xffff0000, v237
	v_lshlrev_b32_e32 v92, 16, v238
	v_and_b32_e32 v93, 0xffff0000, v238
	v_lshlrev_b32_e32 v94, 16, v239
	v_and_b32_e32 v95, 0xffff0000, v239
	v_pk_fma_f32 v[76:77], v[134:135], v[76:77], v[78:79]
	v_pk_fma_f32 v[78:79], v[132:133], v[106:107], v[74:75]
	v_pk_fma_f32 v[72:73], v[130:131], v[72:73], v[94:95]
	v_pk_fma_f32 v[74:75], v[128:129], v[108:109], v[92:93]
	v_cvt_pk_bf16_f32 v92, v78, v79
	v_cvt_pk_bf16_f32 v93, v76, v77
	v_cvt_pk_bf16_f32 v95, v72, v73
	v_mov_b32_e32 v106, v152
	v_cvt_pk_bf16_f32 v94, v74, v75
	global_store_dwordx4 v[98:99], v[92:95], off
	ds_read_b32 v98, v138 offset:4800
	v_ashrrev_i32_e32 v103, 31, v102
	v_lshlrev_b64 v[92:93], 11, v[102:103]
	v_lshl_add_u64 v[92:93], s[0:1], 0, v[92:93]
	v_lshl_add_u64 v[102:103], v[92:93], 0, v[148:149]
	s_waitcnt lgkmcnt(0)
;   __device__ __forceinline__ bf16* h() const { unsigned o_ = (unsigned)(OFF_h); asm volatile("" : "+s"(o_)); return (bf16*)(ws + o_); }
;   __device__ __forceinline__ bf16* y() const { unsigned o_ = (unsigned)(OFF_y); asm volatile("" : "+s"(o_)); return (bf16*)(ws + o_); }
; __device__ __forceinline__ unsigned pk2(float a, float b) { unsigned r; asm("v_cvt_pk_bf16_f32 %0, %1, %2" : "=v"(r) : "v"(a), "v"(b)); return r; }
; __device__ __forceinline__ float lo16(unsigned v) { return __uint_as_float(v << 16); }
; __device__ __forceinline__ float hi16(unsigned v) { return __uint_as_float(v & 0xffff0000u); }
;   __device__ __forceinline__ void fused(f32x4 (&acc)[2][2][4][2], const pg8::Unit& u, int wr, int wc, int fr, int fq, PG8_LAS unsigned char* lds, int wid,
;                                         int lane) const {
;     ...
;       for (int ai = 0; ai < 2; ++ai)
; #pragma unroll
;         for (int m = 0; m < 4; ++m) {
;           const int rl = ai * 128 + wr * 64 + m * 16 + fr;
;           int r = u.pm * 256 + rl;
;           asm volatile("" : "+v"(r));
;           const float rs = rsv[rl];
;           const uint4 hb_ = *(const uint4*)(h + (size_t)r * D + c);
;           const f32x4 hv0 = f32x4{lo16(hb_.x), hi16(hb_.x), lo16(hb_.y), hi16(hb_.y)};
;           const f32x4 hv1 = f32x4{lo16(hb_.z), hi16(hb_.z), lo16(hb_.w), hi16(hb_.w)};
;           const f32x4 nv0 = hv0 + acc[ai][bj][m][0] * rs * gp0;
;           const f32x4 nv1 = hv1 + acc[ai][bj][m][1] * rs * gp1;
;           acc[ai][bj][m][0] = nv0; acc[ai][bj][m][1] = nv1;
;           if (!LAST) {
;             uint4 ho_; ho_.x = pk2(nv0[0], nv0[1]); ho_.y = pk2(nv0[2], nv0[3]); ho_.z = pk2(nv1[0], nv1[1]); ho_.w = pk2(nv1[2], nv1[3]);
;             *(uint4*)(h + (size_t)r * D + c) = ho_;
	v_pk_mul_f32 v[68:69], v[68:69], v[98:99] op_sel_hi:[1,0]
	v_pk_mul_f32 v[70:71], v[70:71], v[98:99] op_sel_hi:[1,0]
	v_pk_mul_f32 v[64:65], v[64:65], v[98:99] op_sel_hi:[1,0]
	v_pk_mul_f32 v[66:67], v[66:67], v[98:99] op_sel_hi:[1,0]
	v_lshlrev_b32_e32 v100, 16, v240
	v_and_b32_e32 v101, 0xffff0000, v240
	v_lshlrev_b32_e32 v92, 16, v241
	v_and_b32_e32 v93, 0xffff0000, v241
	v_lshlrev_b32_e32 v108, 16, v242
	v_and_b32_e32 v109, 0xffff0000, v242
	v_lshlrev_b32_e32 v94, 16, v243
	v_and_b32_e32 v95, 0xffff0000, v243
	v_pk_fma_f32 v[98:99], v[134:135], v[70:71], v[92:93]
	v_pk_fma_f32 v[100:101], v[132:133], v[68:69], v[100:101]
	v_pk_fma_f32 v[92:93], v[130:131], v[66:67], v[94:95]
	v_pk_fma_f32 v[94:95], v[128:129], v[64:65], v[108:109]
	v_cvt_pk_bf16_f32 v64, v100, v101
	v_cvt_pk_bf16_f32 v65, v98, v99
	v_cvt_pk_bf16_f32 v67, v92, v93
	v_mov_b32_e32 v130, v150
	v_cvt_pk_bf16_f32 v66, v94, v95
	global_store_dwordx4 v[102:103], v[64:67], off
	global_load_dwordx4 v[64:67], v[186:187], off offset:528
	s_nop 0
	global_load_dwordx4 v[68:71], v[186:187], off offset:512
	s_nop 0
	v_ashrrev_i32_e32 v107, 31, v106
	v_lshlrev_b64 v[102:103], 11, v[106:107]
	v_lshl_add_u64 v[102:103], s[0:1], 0, v[102:103]
	v_lshl_add_u64 v[128:129], v[102:103], 0, v[148:149]
	v_mov_b32_e32 v244, v152
	v_ashrrev_i32_e32 v245, 31, v244
	v_lshlrev_b64 v[244:245], 11, v[244:245]
	v_lshl_add_u64 v[244:245], s[0:1], 0, v[244:245]
	v_lshl_add_u64 v[244:245], v[244:245], 0, v[148:149]
	global_load_dwordx4 v[212:215], v[244:245], off offset:256
	v_add_u32_e32 v244, 0x10, v152
	v_ashrrev_i32_e32 v245, 31, v244
	v_lshlrev_b64 v[244:245], 11, v[244:245]
	v_lshl_add_u64 v[244:245], s[0:1], 0, v[244:245]
	v_lshl_add_u64 v[244:245], v[244:245], 0, v[148:149]
	global_load_dwordx4 v[216:219], v[244:245], off offset:256
	v_add_u32_e32 v244, 0x20, v152
	v_ashrrev_i32_e32 v245, 31, v244
	v_lshlrev_b64 v[244:245], 11, v[244:245]
	v_lshl_add_u64 v[244:245], s[0:1], 0, v[244:245]
	v_lshl_add_u64 v[244:245], v[244:245], 0, v[148:149]
	global_load_dwordx4 v[220:223], v[244:245], off offset:256
	v_add_u32_e32 v244, 0x30, v152
	v_ashrrev_i32_e32 v245, 31, v244
	v_lshlrev_b64 v[244:245], 11, v[244:245]
	v_lshl_add_u64 v[244:245], s[0:1], 0, v[244:245]
	v_lshl_add_u64 v[244:245], v[244:245], 0, v[148:149]
	global_load_dwordx4 v[224:227], v[244:245], off offset:256
	v_add_u32_e32 v244, 0x80, v152
	v_ashrrev_i32_e32 v245, 31, v244
	v_lshlrev_b64 v[244:245], 11, v[244:245]
	v_lshl_add_u64 v[244:245], s[0:1], 0, v[244:245]
	v_lshl_add_u64 v[244:245], v[244:245], 0, v[148:149]
	global_load_dwordx4 v[228:231], v[244:245], off offset:256
	v_add_u32_e32 v244, 0x90, v152
	v_ashrrev_i32_e32 v245, 31, v244
	v_lshlrev_b64 v[244:245], 11, v[244:245]
	v_lshl_add_u64 v[244:245], s[0:1], 0, v[244:245]
	v_lshl_add_u64 v[244:245], v[244:245], 0, v[148:149]
	global_load_dwordx4 v[232:235], v[244:245], off offset:256
	v_add_u32_e32 v244, 0xa0, v152
	v_ashrrev_i32_e32 v245, 31, v244
	v_lshlrev_b64 v[244:245], 11, v[244:245]
	v_lshl_add_u64 v[244:245], s[0:1], 0, v[244:245]
	v_lshl_add_u64 v[244:245], v[244:245], 0, v[148:149]
	global_load_dwordx4 v[236:239], v[244:245], off offset:256
	v_add_u32_e32 v244, 0xb0, v152
	v_ashrrev_i32_e32 v245, 31, v244
	v_lshlrev_b64 v[244:245], 11, v[244:245]
	v_lshl_add_u64 v[244:245], s[0:1], 0, v[244:245]
	v_lshl_add_u64 v[244:245], v[244:245], 0, v[148:149]
	global_load_dwordx4 v[240:243], v[244:245], off offset:256
	ds_read_b32 v102, v138 offset:4096
	s_waitcnt lgkmcnt(0)
	v_pk_mul_f32 v[60:61], v[60:61], v[102:103] op_sel_hi:[1,0]
	v_pk_mul_f32 v[62:63], v[62:63], v[102:103] op_sel_hi:[1,0]
	v_pk_mul_f32 v[56:57], v[56:57], v[102:103] op_sel_hi:[1,0]
	v_pk_mul_f32 v[58:59], v[58:59], v[102:103] op_sel_hi:[1,0]
	s_waitcnt vmcnt(0)
	v_lshlrev_b32_e32 v102, 16, v212
	v_and_b32_e32 v103, 0xffff0000, v212
	v_lshlrev_b32_e32 v106, 16, v213
	v_and_b32_e32 v107, 0xffff0000, v213
	v_lshlrev_b32_e32 v132, 16, v214
	v_and_b32_e32 v133, 0xffff0000, v214
	v_lshlrev_b32_e32 v134, 16, v215
	v_and_b32_e32 v135, 0xffff0000, v215
	v_pk_fma_f32 v[108:109], v[70:71], v[62:63], v[106:107]
	v_pk_fma_f32 v[110:111], v[68:69], v[60:61], v[102:103]
	v_pk_fma_f32 v[102:103], v[66:67], v[58:59], v[134:135]
	v_pk_fma_f32 v[106:107], v[64:65], v[56:57], v[132:133]
	v_cvt_pk_bf16_f32 v56, v110, v111
	v_cvt_pk_bf16_f32 v57, v108, v109
	v_cvt_pk_bf16_f32 v59, v102, v103
	s_nop 0
	v_cvt_pk_bf16_f32 v58, v106, v107
	global_store_dwordx4 v[128:129], v[56:59], off offset:256
	ds_read_b32 v60, v138 offset:4160
	v_ashrrev_i32_e32 v131, 31, v130
	v_lshlrev_b64 v[56:57], 11, v[130:131]
	v_lshl_add_u64 v[56:57], s[0:1], 0, v[56:57]
	v_lshl_add_u64 v[128:129], v[56:57], 0, v[148:149]
	v_mov_b32_e32 v130, v120
	s_waitcnt lgkmcnt(0)
	v_pk_mul_f32 v[52:53], v[52:53], v[60:61] op_sel_hi:[1,0]
	v_pk_mul_f32 v[54:55], v[54:55], v[60:61] op_sel_hi:[1,0]
	v_pk_mul_f32 v[48:49], v[48:49], v[60:61] op_sel_hi:[1,0]
	v_pk_mul_f32 v[50:51], v[50:51], v[60:61] op_sel_hi:[1,0]
	v_lshlrev_b32_e32 v62, 16, v216
	v_and_b32_e32 v63, 0xffff0000, v216
	v_lshlrev_b32_e32 v56, 16, v217
	v_and_b32_e32 v57, 0xffff0000, v217
	v_lshlrev_b32_e32 v132, 16, v218
	v_and_b32_e32 v133, 0xffff0000, v218
	v_lshlrev_b32_e32 v58, 16, v219
	v_and_b32_e32 v59, 0xffff0000, v219
	v_pk_fma_f32 v[60:61], v[70:71], v[54:55], v[56:57]
	v_pk_fma_f32 v[62:63], v[68:69], v[52:53], v[62:63]
	v_pk_fma_f32 v[56:57], v[66:67], v[50:51], v[58:59]
	v_pk_fma_f32 v[58:59], v[64:65], v[48:49], v[132:133]
	v_cvt_pk_bf16_f32 v48, v62, v63
	v_cvt_pk_bf16_f32 v49, v60, v61
	v_cvt_pk_bf16_f32 v51, v56, v57
	s_nop 0
	v_cvt_pk_bf16_f32 v50, v58, v59
	global_store_dwordx4 v[128:129], v[48:51], off offset:256
	ds_read_b32 v54, v138 offset:4224
	v_ashrrev_i32_e32 v131, 31, v130
	v_lshlrev_b64 v[48:49], 11, v[130:131]
	v_lshl_add_u64 v[48:49], s[0:1], 0, v[48:49]
	v_lshl_add_u64 v[52:53], v[48:49], 0, v[148:149]
	v_mov_b32_e32 v128, v112
	s_waitcnt lgkmcnt(0)
;   __device__ __forceinline__ bf16* h() const { unsigned o_ = (unsigned)(OFF_h); asm volatile("" : "+s"(o_)); return (bf16*)(ws + o_); }
;   __device__ __forceinline__ bf16* y() const { unsigned o_ = (unsigned)(OFF_y); asm volatile("" : "+s"(o_)); return (bf16*)(ws + o_); }
; __device__ __forceinline__ unsigned pk2(float a, float b) { unsigned r; asm("v_cvt_pk_bf16_f32 %0, %1, %2" : "=v"(r) : "v"(a), "v"(b)); return r; }
; __device__ __forceinline__ float lo16(unsigned v) { return __uint_as_float(v << 16); }
; __device__ __forceinline__ float hi16(unsigned v) { return __uint_as_float(v & 0xffff0000u); }
;   __device__ __forceinline__ void fused(f32x4 (&acc)[2][2][4][2], const pg8::Unit& u, int wr, int wc, int fr, int fq, PG8_LAS unsigned char* lds, int wid,
;                                         int lane) const {
;     ...
;       for (int ai = 0; ai < 2; ++ai)
; #pragma unroll
;         for (int m = 0; m < 4; ++m) {
;           const int rl = ai * 128 + wr * 64 + m * 16 + fr;
;           int r = u.pm * 256 + rl;
;           asm volatile("" : "+v"(r));
;           const float rs = rsv[rl];
;           const uint4 hb_ = *(const uint4*)(h + (size_t)r * D + c);
;           const f32x4 hv0 = f32x4{lo16(hb_.x), hi16(hb_.x), lo16(hb_.y), hi16(hb_.y)};
;           const f32x4 hv1 = f32x4{lo16(hb_.z), hi16(hb_.z), lo16(hb_.w), hi16(hb_.w)};
;           const f32x4 nv0 = hv0 + acc[ai][bj][m][0] * rs * gp0;
;           const f32x4 nv1 = hv1 + acc[ai][bj][m][1] * rs * gp1;
;           acc[ai][bj][m][0] = nv0; acc[ai][bj][m][1] = nv1;
;           if (!LAST) {
;             uint4 ho_; ho_.x = pk2(nv0[0], nv0[1]); ho_.y = pk2(nv0[2], nv0[3]); ho_.z = pk2(nv1[0], nv1[1]); ho_.w = pk2(nv1[2], nv1[3]);
;             *(uint4*)(h + (size_t)r * D + c) = ho_;
	v_pk_mul_f32 v[130:131], v[44:45], v[54:55] op_sel_hi:[1,0]
	v_pk_mul_f32 v[44:45], v[46:47], v[54:55] op_sel_hi:[1,0]
	v_pk_mul_f32 v[132:133], v[40:41], v[54:55] op_sel_hi:[1,0]
	v_pk_mul_f32 v[40:41], v[42:43], v[54:55] op_sel_hi:[1,0]
	v_lshlrev_b32_e32 v42, 16, v220
	v_and_b32_e32 v43, 0xffff0000, v220
	v_lshlrev_b32_e32 v46, 16, v221
	v_and_b32_e32 v47, 0xffff0000, v221
	v_lshlrev_b32_e32 v48, 16, v222
	v_and_b32_e32 v49, 0xffff0000, v222
	v_lshlrev_b32_e32 v50, 16, v223
	v_and_b32_e32 v51, 0xffff0000, v223
	v_pk_fma_f32 v[44:45], v[70:71], v[44:45], v[46:47]
	v_pk_fma_f32 v[46:47], v[68:69], v[130:131], v[42:43]
	v_pk_fma_f32 v[40:41], v[66:67], v[40:41], v[50:51]
	v_pk_fma_f32 v[42:43], v[64:65], v[132:133], v[48:49]
	v_cvt_pk_bf16_f32 v48, v46, v47
	v_cvt_pk_bf16_f32 v49, v44, v45
	v_cvt_pk_bf16_f32 v51, v40, v41
	s_nop 0
	v_cvt_pk_bf16_f32 v50, v42, v43
	global_store_dwordx4 v[52:53], v[48:51], off offset:256
	ds_read_b32 v54, v138 offset:4288
	v_ashrrev_i32_e32 v129, 31, v128
	v_lshlrev_b64 v[48:49], 11, v[128:129]
	v_lshl_add_u64 v[48:49], s[0:1], 0, v[48:49]
	v_lshl_add_u64 v[52:53], v[48:49], 0, v[148:149]
	v_mov_b32_e32 v128, v104
	s_waitcnt lgkmcnt(0)
	v_pk_mul_f32 v[130:131], v[36:37], v[54:55] op_sel_hi:[1,0]
	v_pk_mul_f32 v[36:37], v[38:39], v[54:55] op_sel_hi:[1,0]
	v_pk_mul_f32 v[132:133], v[32:33], v[54:55] op_sel_hi:[1,0]
	v_pk_mul_f32 v[32:33], v[34:35], v[54:55] op_sel_hi:[1,0]
	v_lshlrev_b32_e32 v34, 16, v224
	v_and_b32_e32 v35, 0xffff0000, v224
	v_lshlrev_b32_e32 v38, 16, v225
	v_and_b32_e32 v39, 0xffff0000, v225
	v_lshlrev_b32_e32 v48, 16, v226
	v_and_b32_e32 v49, 0xffff0000, v226
	v_lshlrev_b32_e32 v50, 16, v227
	v_and_b32_e32 v51, 0xffff0000, v227
	v_pk_fma_f32 v[36:37], v[70:71], v[36:37], v[38:39]
	v_pk_fma_f32 v[38:39], v[68:69], v[130:131], v[34:35]
	v_pk_fma_f32 v[32:33], v[66:67], v[32:33], v[50:51]
	v_pk_fma_f32 v[34:35], v[64:65], v[132:133], v[48:49]
	v_cvt_pk_bf16_f32 v48, v38, v39
	v_cvt_pk_bf16_f32 v49, v36, v37
	v_cvt_pk_bf16_f32 v51, v32, v33
	s_nop 0
	v_cvt_pk_bf16_f32 v50, v34, v35
	global_store_dwordx4 v[52:53], v[48:51], off offset:256
	ds_read_b32 v54, v138 offset:4608
	v_ashrrev_i32_e32 v129, 31, v128
	v_lshlrev_b64 v[48:49], 11, v[128:129]
	v_lshl_add_u64 v[48:49], s[0:1], 0, v[48:49]
	v_lshl_add_u64 v[52:53], v[48:49], 0, v[148:149]
	v_mov_b32_e32 v128, v96
	s_waitcnt lgkmcnt(0)
	v_pk_mul_f32 v[130:131], v[28:29], v[54:55] op_sel_hi:[1,0]
	v_pk_mul_f32 v[28:29], v[30:31], v[54:55] op_sel_hi:[1,0]
	v_pk_mul_f32 v[24:25], v[24:25], v[54:55] op_sel_hi:[1,0]
	v_pk_mul_f32 v[26:27], v[26:27], v[54:55] op_sel_hi:[1,0]
	v_lshlrev_b32_e32 v30, 16, v228
	v_and_b32_e32 v31, 0xffff0000, v228
	v_lshlrev_b32_e32 v48, 16, v229
	v_and_b32_e32 v49, 0xffff0000, v229
	v_lshlrev_b32_e32 v54, 16, v230
	v_and_b32_e32 v55, 0xffff0000, v230
	v_lshlrev_b32_e32 v50, 16, v231
	v_and_b32_e32 v51, 0xffff0000, v231
	v_pk_fma_f32 v[28:29], v[70:71], v[28:29], v[48:49]
	v_pk_fma_f32 v[30:31], v[68:69], v[130:131], v[30:31]
	v_pk_fma_f32 v[26:27], v[66:67], v[26:27], v[50:51]
	v_pk_fma_f32 v[24:25], v[64:65], v[24:25], v[54:55]
	v_cvt_pk_bf16_f32 v48, v30, v31
	v_cvt_pk_bf16_f32 v49, v28, v29
	v_cvt_pk_bf16_f32 v51, v26, v27
	s_nop 0
	v_cvt_pk_bf16_f32 v50, v24, v25
	global_store_dwordx4 v[52:53], v[48:51], off offset:256
	ds_read_b32 v54, v138 offset:4672
	v_ashrrev_i32_e32 v129, 31, v128
	v_lshlrev_b64 v[48:49], 11, v[128:129]
	v_lshl_add_u64 v[48:49], s[0:1], 0, v[48:49]
	v_lshl_add_u64 v[52:53], v[48:49], 0, v[148:149]
	v_mov_b32_e32 v128, v88
	s_waitcnt lgkmcnt(0)
	v_pk_mul_f32 v[130:131], v[20:21], v[54:55] op_sel_hi:[1,0]
	v_pk_mul_f32 v[20:21], v[22:23], v[54:55] op_sel_hi:[1,0]
	v_pk_mul_f32 v[132:133], v[16:17], v[54:55] op_sel_hi:[1,0]
	v_pk_mul_f32 v[16:17], v[18:19], v[54:55] op_sel_hi:[1,0]
	v_lshlrev_b32_e32 v18, 16, v232
	v_and_b32_e32 v19, 0xffff0000, v232
	v_lshlrev_b32_e32 v22, 16, v233
	v_and_b32_e32 v23, 0xffff0000, v233
	v_lshlrev_b32_e32 v48, 16, v234
	v_and_b32_e32 v49, 0xffff0000, v234
	v_lshlrev_b32_e32 v50, 16, v235
	v_and_b32_e32 v51, 0xffff0000, v235
	v_pk_fma_f32 v[20:21], v[70:71], v[20:21], v[22:23]
	v_pk_fma_f32 v[22:23], v[68:69], v[130:131], v[18:19]
	v_pk_fma_f32 v[16:17], v[66:67], v[16:17], v[50:51]
	v_pk_fma_f32 v[18:19], v[64:65], v[132:133], v[48:49]
	v_cvt_pk_bf16_f32 v48, v22, v23
	v_cvt_pk_bf16_f32 v49, v20, v21
	v_cvt_pk_bf16_f32 v51, v16, v17
	s_nop 0
	v_cvt_pk_bf16_f32 v50, v18, v19
	global_store_dwordx4 v[52:53], v[48:51], off offset:256
	ds_read_b32 v54, v138 offset:4736
	v_ashrrev_i32_e32 v129, 31, v128
	v_lshlrev_b64 v[48:49], 11, v[128:129]
	v_lshl_add_u64 v[48:49], s[0:1], 0, v[48:49]
	v_lshl_add_u64 v[52:53], v[48:49], 0, v[148:149]
	v_mov_b32_e32 v128, v80
	s_waitcnt lgkmcnt(0)
;   __device__ __forceinline__ bf16* h() const { unsigned o_ = (unsigned)(OFF_h); asm volatile("" : "+s"(o_)); return (bf16*)(ws + o_); }
;   __device__ __forceinline__ bf16* y() const { unsigned o_ = (unsigned)(OFF_y); asm volatile("" : "+s"(o_)); return (bf16*)(ws + o_); }
; __device__ __forceinline__ unsigned pk2(float a, float b) { unsigned r; asm("v_cvt_pk_bf16_f32 %0, %1, %2" : "=v"(r) : "v"(a), "v"(b)); return r; }
;   __device__ __forceinline__ void exchange(const f32x4 (&acc)[2][2][4][2], const pg8::Unit& u, int wr, int wc, int fr, int fq, PG8_LAS float* ssq,
;                                            PG8_LAS float* rsv, int tid, float* ex, unsigned* cnt) const {
; #pragma unroll
;     for (int ai = 0; ai < 2; ++ai)
; #pragma unroll
;       for (int m = 0; m < 4; ++m) {
;         float sv = 0.f;
; #pragma unroll
;         for (int bj = 0; bj < 2; ++bj)
; #pragma unroll
;           for (int n = 0; n < 2; ++n) {
;             const f32x4 a = acc[ai][bj][m][n];
;             sv += a[0] * a[0] + a[1] * a[1] + a[2] * a[2] + a[3] * a[3];
;           }
;         sv += __shfl_xor(sv, 16); sv += __shfl_xor(sv, 32);
;         if (fq == 0) ssq[wc * 256 + ai * 128 + wr * 64 + m * 16 + fr] = sv;
;       }
;   __device__ __forceinline__ void fused(f32x4 (&acc)[2][2][4][2], const pg8::Unit& u, int wr, int wc, int fr, int fq, PG8_LAS unsigned char* lds, int wid,
;                                         int lane) const {
;     ...
;       for (int ai = 0; ai < 2; ++ai)
; #pragma unroll
;         for (int m = 0; m < 4; ++m) {
;           const int rl = ai * 128 + wr * 64 + m * 16 + fr;
;           int r = u.pm * 256 + rl;
;           asm volatile("" : "+v"(r));
;           const float rs = rsv[rl];
;           const uint4 hb_ = *(const uint4*)(h + (size_t)r * D + c);
;           const f32x4 hv0 = f32x4{lo16(hb_.x), hi16(hb_.x), lo16(hb_.y), hi16(hb_.y)};
;           const f32x4 hv1 = f32x4{lo16(hb_.z), hi16(hb_.z), lo16(hb_.w), hi16(hb_.w)};
;           const f32x4 nv0 = hv0 + acc[ai][bj][m][0] * rs * gp0;
;           const f32x4 nv1 = hv1 + acc[ai][bj][m][1] * rs * gp1;
;           acc[ai][bj][m][0] = nv0; acc[ai][bj][m][1] = nv1;
;           if (!LAST) {
;             uint4 ho_; ho_.x = pk2(nv0[0], nv0[1]); ho_.y = pk2(nv0[2], nv0[3]); ho_.z = pk2(nv1[0], nv1[1]); ho_.w = pk2(nv1[2], nv1[3]);
;             *(uint4*)(h + (size_t)r * D + c) = ho_;
	v_pk_mul_f32 v[130:131], v[12:13], v[54:55] op_sel_hi:[1,0]
	v_pk_mul_f32 v[12:13], v[14:15], v[54:55] op_sel_hi:[1,0]
	v_pk_mul_f32 v[132:133], v[8:9], v[54:55] op_sel_hi:[1,0]
	v_pk_mul_f32 v[8:9], v[10:11], v[54:55] op_sel_hi:[1,0]
	v_mul_f32_e32 v54, v107, v107
	v_fmac_f32_e32 v54, v106, v106
	v_fmac_f32_e32 v54, v102, v102
	v_fmac_f32_e32 v54, v103, v103
	v_lshlrev_b32_e32 v10, 16, v236
	v_and_b32_e32 v11, 0xffff0000, v236
	v_lshlrev_b32_e32 v14, 16, v237
	v_and_b32_e32 v15, 0xffff0000, v237
	v_lshlrev_b32_e32 v48, 16, v238
	v_and_b32_e32 v49, 0xffff0000, v238
	v_lshlrev_b32_e32 v50, 16, v239
	v_and_b32_e32 v51, 0xffff0000, v239
	v_pk_fma_f32 v[12:13], v[70:71], v[12:13], v[14:15]
	v_pk_fma_f32 v[14:15], v[68:69], v[130:131], v[10:11]
	v_pk_fma_f32 v[8:9], v[66:67], v[8:9], v[50:51]
	v_pk_fma_f32 v[10:11], v[64:65], v[132:133], v[48:49]
	v_cvt_pk_bf16_f32 v48, v14, v15
	v_cvt_pk_bf16_f32 v49, v12, v13
	v_cvt_pk_bf16_f32 v51, v8, v9
	s_nop 0
	v_cvt_pk_bf16_f32 v50, v10, v11
	global_store_dwordx4 v[52:53], v[48:51], off offset:256
	v_mul_f32_e32 v52, v185, v185
	v_ashrrev_i32_e32 v129, 31, v128
	v_lshlrev_b64 v[48:49], 11, v[128:129]
	v_lshl_add_u64 v[48:49], s[0:1], 0, v[48:49]
	v_lshl_add_u64 v[128:129], v[48:49], 0, v[148:149]
	v_mul_f32_e32 v53, v181, v181
	v_fmac_f32_e32 v52, v184, v184
	v_fmac_f32_e32 v53, v180, v180
	v_fmac_f32_e32 v52, v182, v182
	v_fmac_f32_e32 v53, v178, v178
	v_fmac_f32_e32 v52, v183, v183
	v_fmac_f32_e32 v53, v179, v179
	v_add_f32_e32 v52, v52, v53
	v_mul_f32_e32 v53, v111, v111
	v_fmac_f32_e32 v53, v110, v110
	v_fmac_f32_e32 v53, v108, v108
	v_fmac_f32_e32 v53, v109, v109
	v_add_f32_e32 v52, v52, v53
	v_add_f32_e32 v53, v52, v54
	ds_bpermute_b32 v54, v151, v53
	ds_read_b32 v52, v138 offset:4800
	s_waitcnt lgkmcnt(1)
	v_add_f32_e32 v81, v53, v54
	ds_bpermute_b32 v89, v209, v81
	s_waitcnt lgkmcnt(1)
	v_pk_mul_f32 v[4:5], v[4:5], v[52:53] op_sel_hi:[1,0]
	v_pk_mul_f32 v[6:7], v[6:7], v[52:53] op_sel_hi:[1,0]
	v_pk_mul_f32 v[0:1], v[0:1], v[52:53] op_sel_hi:[1,0]
	v_pk_mul_f32 v[2:3], v[2:3], v[52:53] op_sel_hi:[1,0]
	v_lshlrev_b32_e32 v54, 16, v240
	v_and_b32_e32 v55, 0xffff0000, v240
	v_lshlrev_b32_e32 v48, 16, v241
	v_and_b32_e32 v49, 0xffff0000, v241
	v_lshlrev_b32_e32 v130, 16, v242
	v_and_b32_e32 v131, 0xffff0000, v242
	v_lshlrev_b32_e32 v50, 16, v243
	v_and_b32_e32 v51, 0xffff0000, v243
	v_pk_fma_f32 v[52:53], v[70:71], v[6:7], v[48:49]
	v_pk_fma_f32 v[54:55], v[68:69], v[4:5], v[54:55]
	v_pk_fma_f32 v[48:49], v[66:67], v[2:3], v[50:51]
	v_pk_fma_f32 v[50:51], v[64:65], v[0:1], v[130:131]
	v_cvt_pk_bf16_f32 v0, v54, v55
	v_cvt_pk_bf16_f32 v1, v52, v53
	v_cvt_pk_bf16_f32 v3, v48, v49
	s_nop 0
	v_cvt_pk_bf16_f32 v2, v50, v51
	global_store_dwordx4 v[128:129], v[0:3], off offset:256
	s_waitcnt lgkmcnt(0)
	s_barrier
	s_and_saveexec_b64 s[0:1], s[2:3]
	v_add_f32_e32 v0, v81, v89
	ds_write_b32 v153, v0
	s_or_b64 exec, exec, s[0:1]
	v_mul_f32_e32 v0, v177, v177
	v_mul_f32_e32 v1, v173, v173
	v_fmac_f32_e32 v0, v176, v176
	v_fmac_f32_e32 v1, v172, v172
	v_fmac_f32_e32 v0, v174, v174
	v_fmac_f32_e32 v1, v170, v170
	v_fmac_f32_e32 v0, v175, v175
	v_fmac_f32_e32 v1, v171, v171
	v_add_f32_e32 v0, v0, v1
	v_mul_f32_e32 v1, v63, v63
	v_fmac_f32_e32 v1, v62, v62
	v_fmac_f32_e32 v1, v60, v60
	v_fmac_f32_e32 v1, v61, v61
	v_add_f32_e32 v0, v0, v1
	v_mul_f32_e32 v1, v59, v59
	v_fmac_f32_e32 v1, v58, v58
	v_fmac_f32_e32 v1, v56, v56
	v_fmac_f32_e32 v1, v57, v57
	v_add_f32_e32 v0, v0, v1
	ds_bpermute_b32 v1, v151, v0
	s_waitcnt lgkmcnt(0)
	v_add_f32_e32 v0, v0, v1
	ds_bpermute_b32 v1, v209, v0
	s_and_saveexec_b64 s[0:1], s[2:3]
	s_cbranch_execz .LBB0_845
	s_waitcnt lgkmcnt(0)
	v_add_f32_e32 v0, v0, v1
	ds_write_b32 v153, v0 offset:64

;   __device__ __forceinline__ bf16* h() const { unsigned o_ = (unsigned)(OFF_h); asm volatile("" : "+s"(o_)); return (bf16*)(ws + o_); }
;   __device__ __forceinline__ bf16* y() const { unsigned o_ = (unsigned)(OFF_y); asm volatile("" : "+s"(o_)); return (bf16*)(ws + o_); }
; __device__ __forceinline__ unsigned pk2(float a, float b) { unsigned r; asm("v_cvt_pk_bf16_f32 %0, %1, %2" : "=v"(r) : "v"(a), "v"(b)); return r; }
; __device__ __forceinline__ float lo16(unsigned v) { return __uint_as_float(v << 16); }
; __device__ __forceinline__ float hi16(unsigned v) { return __uint_as_float(v & 0xffff0000u); }
;   __device__ __forceinline__ void fused(f32x4 (&acc)[2][2][4][2], const pg8::Unit& u, int wr, int wc, int fr, int fq, PG8_LAS unsigned char* lds, int wid,
;                                         int lane) const {
;     ...
;     const int colb = u.pn * 256 + wc * 32 + 8 * fq;
; #pragma unroll
;     for (int bj = 0; bj < 2; ++bj) {
;       const int c = colb + bj * 128;
;       const f32x4 gp0 = *(const f32x4*)(gpost + c), gp1 = *(const f32x4*)(gpost + c + 4);
; #pragma unroll
;       for (int ai = 0; ai < 2; ++ai)
; #pragma unroll
;         for (int m = 0; m < 4; ++m) {
;           const int rl = ai * 128 + wr * 64 + m * 16 + fr;
;           int r = u.pm * 256 + rl;
;           asm volatile("" : "+v"(r));
;           const float rs = rsv[rl];
;           const uint4 hb_ = *(const uint4*)(h + (size_t)r * D + c);
;           const f32x4 hv0 = f32x4{lo16(hb_.x), hi16(hb_.x), lo16(hb_.y), hi16(hb_.y)};
;           const f32x4 hv1 = f32x4{lo16(hb_.z), hi16(hb_.z), lo16(hb_.w), hi16(hb_.w)};
;           const f32x4 nv0 = hv0 + acc[ai][bj][m][0] * rs * gp0;
;           const f32x4 nv1 = hv1 + acc[ai][bj][m][1] * rs * gp1;
;           acc[ai][bj][m][0] = nv0; acc[ai][bj][m][1] = nv1;
;           if (!LAST) {
;             uint4 ho_; ho_.x = pk2(nv0[0], nv0[1]); ho_.y = pk2(nv0[2], nv0[3]); ho_.z = pk2(nv1[0], nv1[1]); ho_.w = pk2(nv1[2], nv1[3]);
;             *(uint4*)(h + (size_t)r * D + c) = ho_;
.LBB0_1112:
	s_or_b64 exec, exec, s[0:1]
	v_readlane_b32 s56, v254, 8
	v_readlane_b32 s57, v254, 9
	v_readlane_b32 s58, v254, 10
	v_readlane_b32 s59, v254, 11
	v_readlane_b32 s60, v254, 12
	v_readlane_b32 s61, v254, 13
	v_readlane_b32 s62, v254, 14
	v_readlane_b32 s63, v254, 15
	v_readlane_b32 s64, v254, 16
	v_readlane_b32 s65, v254, 17
	v_readlane_b32 s66, v254, 18
	v_readlane_b32 s67, v254, 19
	s_add_u32 s0, s76, s30
	v_readlane_b32 s68, v254, 20
	v_readlane_b32 s69, v254, 21
	v_readlane_b32 s70, v254, 22
	v_readlane_b32 s71, v254, 23
	s_mov_b64 s[56:57], s[60:61]
	s_addc_u32 s1, s77, 0
	s_mov_b64 s[58:59], s[62:63]
	s_mov_b64 s[60:61], s[64:65]
	s_mov_b64 s[62:63], s[66:67]
	s_mov_b64 s[56:57], s[18:19]
	s_add_u32 s12, s62, s56
	s_addc_u32 s13, s63, s57
	s_lshl_b32 s17, s31, 5
	s_lshl_b32 s18, s29, 8
	v_lshrrev_b32_e32 v128, 1, v156
	s_or_b32 s17, s18, s17
	v_and_or_b32 v168, v128, 24, s17
	v_lshl_add_u32 v152, s16, 8, v157
	v_ashrrev_i32_e32 v169, 31, v168
	v_lshl_add_u64 v[186:187], v[168:169], 2, s[12:13]
	v_mov_b32_e32 v148, v152
	s_waitcnt lgkmcnt(0)
	s_barrier
	global_load_dwordx4 v[128:131], v[186:187], off offset:16
	global_load_dwordx4 v[132:135], v[186:187], off
	v_lshl_add_u32 v138, v157, 2, v196
	v_ashrrev_i32_e32 v149, 31, v148
	v_lshlrev_b64 v[148:149], 11, v[148:149]
	v_lshl_add_u64 v[158:159], s[0:1], 0, v[148:149]
	v_lshlrev_b64 v[148:149], 1, v[168:169]
	v_lshl_add_u64 v[162:163], v[158:159], 0, v[148:149]
	v_mov_b32_e32 v244, v152
	v_ashrrev_i32_e32 v245, 31, v244
	v_lshlrev_b64 v[244:245], 11, v[244:245]
	v_lshl_add_u64 v[244:245], s[0:1], 0, v[244:245]
	v_lshl_add_u64 v[244:245], v[244:245], 0, v[148:149]
	global_load_dwordx4 v[212:215], v[244:245], off
	v_add_u32_e32 v244, 0x10, v152
	v_ashrrev_i32_e32 v245, 31, v244
	v_lshlrev_b64 v[244:245], 11, v[244:245]
	v_lshl_add_u64 v[244:245], s[0:1], 0, v[244:245]
	v_lshl_add_u64 v[244:245], v[244:245], 0, v[148:149]
	global_load_dwordx4 v[216:219], v[244:245], off
	v_add_u32_e32 v244, 0x20, v152
	v_ashrrev_i32_e32 v245, 31, v244
	v_lshlrev_b64 v[244:245], 11, v[244:245]
	v_lshl_add_u64 v[244:245], s[0:1], 0, v[244:245]
	v_lshl_add_u64 v[244:245], v[244:245], 0, v[148:149]
	global_load_dwordx4 v[220:223], v[244:245], off
	v_add_u32_e32 v244, 0x30, v152
	v_ashrrev_i32_e32 v245, 31, v244
	v_lshlrev_b64 v[244:245], 11, v[244:245]
	v_lshl_add_u64 v[244:245], s[0:1], 0, v[244:245]
	v_lshl_add_u64 v[244:245], v[244:245], 0, v[148:149]
	global_load_dwordx4 v[224:227], v[244:245], off
	v_add_u32_e32 v244, 0x80, v152
	v_ashrrev_i32_e32 v245, 31, v244
	v_lshlrev_b64 v[244:245], 11, v[244:245]
	v_lshl_add_u64 v[244:245], s[0:1], 0, v[244:245]
	v_lshl_add_u64 v[244:245], v[244:245], 0, v[148:149]
	global_load_dwordx4 v[228:231], v[244:245], off
	v_add_u32_e32 v244, 0x90, v152
	v_ashrrev_i32_e32 v245, 31, v244
	v_lshlrev_b64 v[244:245], 11, v[244:245]
	v_lshl_add_u64 v[244:245], s[0:1], 0, v[244:245]
	v_lshl_add_u64 v[244:245], v[244:245], 0, v[148:149]
	global_load_dwordx4 v[232:235], v[244:245], off
	v_add_u32_e32 v244, 0xa0, v152
	v_ashrrev_i32_e32 v245, 31, v244
	v_lshlrev_b64 v[244:245], 11, v[244:245]
	v_lshl_add_u64 v[244:245], s[0:1], 0, v[244:245]
	v_lshl_add_u64 v[244:245], v[244:245], 0, v[148:149]
	global_load_dwordx4 v[236:239], v[244:245], off
	v_add_u32_e32 v244, 0xb0, v152
	v_ashrrev_i32_e32 v245, 31, v244
	v_lshlrev_b64 v[244:245], 11, v[244:245]
	v_lshl_add_u64 v[244:245], s[0:1], 0, v[244:245]
	v_lshl_add_u64 v[244:245], v[244:245], 0, v[148:149]
	global_load_dwordx4 v[240:243], v[244:245], off
	ds_read_b32 v156, v138 offset:4096
	v_add_u32_e32 v150, 16, v152
	v_mov_b32_e32 v164, v150
	s_mov_b64 s[64:65], s[68:69]
	s_mov_b64 s[66:67], s[70:71]
	s_waitcnt lgkmcnt(0)
	v_pk_mul_f32 v[124:125], v[124:125], v[156:157] op_sel_hi:[1,0]
	v_pk_mul_f32 v[126:127], v[126:127], v[156:157] op_sel_hi:[1,0]
	v_pk_mul_f32 v[120:121], v[120:121], v[156:157] op_sel_hi:[1,0]
	v_pk_mul_f32 v[122:123], v[122:123], v[156:157] op_sel_hi:[1,0]
	s_waitcnt vmcnt(0)
	v_lshlrev_b32_e32 v156, 16, v212
	v_and_b32_e32 v157, 0xffff0000, v212
	v_lshlrev_b32_e32 v158, 16, v213
	v_and_b32_e32 v159, 0xffff0000, v213
	v_lshlrev_b32_e32 v166, 16, v214
	v_and_b32_e32 v167, 0xffff0000, v214
	v_lshlrev_b32_e32 v160, 16, v215
	v_and_b32_e32 v161, 0xffff0000, v215
	v_pk_fma_f32 v[182:183], v[134:135], v[126:127], v[158:159]
	v_pk_fma_f32 v[184:185], v[132:133], v[124:125], v[156:157]
	v_pk_fma_f32 v[178:179], v[130:131], v[122:123], v[160:161]
	v_pk_fma_f32 v[180:181], v[128:129], v[120:121], v[166:167]
	v_cvt_pk_bf16_f32 v120, v184, v185
	v_cvt_pk_bf16_f32 v121, v182, v183
	v_cvt_pk_bf16_f32 v123, v178, v179
	s_nop 0
	v_cvt_pk_bf16_f32 v122, v180, v181
	global_store_dwordx4 v[162:163], v[120:123], off
	ds_read_b32 v156, v138 offset:4160
	v_ashrrev_i32_e32 v165, 31, v164
	v_lshlrev_b64 v[120:121], 11, v[164:165]
	v_lshl_add_u64 v[120:121], s[0:1], 0, v[120:121]
	v_lshl_add_u64 v[126:127], v[120:121], 0, v[148:149]
	v_add_u32_e32 v120, 32, v152
	v_mov_b32_e32 v158, v120
	s_waitcnt lgkmcnt(0)
;   __device__ __forceinline__ bf16* h() const { unsigned o_ = (unsigned)(OFF_h); asm volatile("" : "+s"(o_)); return (bf16*)(ws + o_); }
;   __device__ __forceinline__ bf16* y() const { unsigned o_ = (unsigned)(OFF_y); asm volatile("" : "+s"(o_)); return (bf16*)(ws + o_); }
; __device__ __forceinline__ unsigned pk2(float a, float b) { unsigned r; asm("v_cvt_pk_bf16_f32 %0, %1, %2" : "=v"(r) : "v"(a), "v"(b)); return r; }
; __device__ __forceinline__ float lo16(unsigned v) { return __uint_as_float(v << 16); }
; __device__ __forceinline__ float hi16(unsigned v) { return __uint_as_float(v & 0xffff0000u); }
;   __device__ __forceinline__ void fused(f32x4 (&acc)[2][2][4][2], const pg8::Unit& u, int wr, int wc, int fr, int fq, PG8_LAS unsigned char* lds, int wid,
;                                         int lane) const {
;     ...
;       for (int ai = 0; ai < 2; ++ai)
; #pragma unroll
;         for (int m = 0; m < 4; ++m) {
;           const int rl = ai * 128 + wr * 64 + m * 16 + fr;
;           int r = u.pm * 256 + rl;
;           asm volatile("" : "+v"(r));
;           const float rs = rsv[rl];
;           const uint4 hb_ = *(const uint4*)(h + (size_t)r * D + c);
;           const f32x4 hv0 = f32x4{lo16(hb_.x), hi16(hb_.x), lo16(hb_.y), hi16(hb_.y)};
;           const f32x4 hv1 = f32x4{lo16(hb_.z), hi16(hb_.z), lo16(hb_.w), hi16(hb_.w)};
;           const f32x4 nv0 = hv0 + acc[ai][bj][m][0] * rs * gp0;
;           const f32x4 nv1 = hv1 + acc[ai][bj][m][1] * rs * gp1;
;           acc[ai][bj][m][0] = nv0; acc[ai][bj][m][1] = nv1;
;           if (!LAST) {
;             uint4 ho_; ho_.x = pk2(nv0[0], nv0[1]); ho_.y = pk2(nv0[2], nv0[3]); ho_.z = pk2(nv1[0], nv1[1]); ho_.w = pk2(nv1[2], nv1[3]);
;             *(uint4*)(h + (size_t)r * D + c) = ho_;
	v_pk_mul_f32 v[116:117], v[116:117], v[156:157] op_sel_hi:[1,0]
	v_pk_mul_f32 v[118:119], v[118:119], v[156:157] op_sel_hi:[1,0]
	v_pk_mul_f32 v[112:113], v[112:113], v[156:157] op_sel_hi:[1,0]
	v_pk_mul_f32 v[114:115], v[114:115], v[156:157] op_sel_hi:[1,0]
	v_lshlrev_b32_e32 v156, 16, v216
	v_and_b32_e32 v157, 0xffff0000, v216
	v_lshlrev_b32_e32 v122, 16, v217
	v_and_b32_e32 v123, 0xffff0000, v217
	v_lshlrev_b32_e32 v160, 16, v218
	v_and_b32_e32 v161, 0xffff0000, v218
	v_lshlrev_b32_e32 v124, 16, v219
	v_and_b32_e32 v125, 0xffff0000, v219
	v_pk_fma_f32 v[174:175], v[134:135], v[118:119], v[122:123]
	v_pk_fma_f32 v[176:177], v[132:133], v[116:117], v[156:157]
	v_pk_fma_f32 v[170:171], v[130:131], v[114:115], v[124:125]
	v_pk_fma_f32 v[172:173], v[128:129], v[112:113], v[160:161]
	v_cvt_pk_bf16_f32 v112, v176, v177
	v_cvt_pk_bf16_f32 v113, v174, v175
	v_cvt_pk_bf16_f32 v115, v170, v171
	s_nop 0
	v_cvt_pk_bf16_f32 v114, v172, v173
	global_store_dwordx4 v[126:127], v[112:115], off
	ds_read_b32 v122, v138 offset:4224
	v_ashrrev_i32_e32 v159, 31, v158
	v_lshlrev_b64 v[112:113], 11, v[158:159]
	v_lshl_add_u64 v[112:113], s[0:1], 0, v[112:113]
	v_lshl_add_u64 v[118:119], v[112:113], 0, v[148:149]
	v_add_u32_e32 v112, 48, v152
	v_mov_b32_e32 v124, v112
	s_waitcnt lgkmcnt(0)
	v_pk_mul_f32 v[108:109], v[108:109], v[122:123] op_sel_hi:[1,0]
	v_pk_mul_f32 v[110:111], v[110:111], v[122:123] op_sel_hi:[1,0]
	v_pk_mul_f32 v[104:105], v[104:105], v[122:123] op_sel_hi:[1,0]
	v_pk_mul_f32 v[106:107], v[106:107], v[122:123] op_sel_hi:[1,0]
	v_lshlrev_b32_e32 v122, 16, v220
	v_and_b32_e32 v123, 0xffff0000, v220
	v_lshlrev_b32_e32 v114, 16, v221
	v_and_b32_e32 v115, 0xffff0000, v221
	v_lshlrev_b32_e32 v126, 16, v222
	v_and_b32_e32 v127, 0xffff0000, v222
	v_lshlrev_b32_e32 v116, 16, v223
	v_and_b32_e32 v117, 0xffff0000, v223
	v_pk_fma_f32 v[164:165], v[134:135], v[110:111], v[114:115]
	v_pk_fma_f32 v[166:167], v[132:133], v[108:109], v[122:123]
	v_pk_fma_f32 v[160:161], v[130:131], v[106:107], v[116:117]
	v_pk_fma_f32 v[162:163], v[128:129], v[104:105], v[126:127]
	v_cvt_pk_bf16_f32 v104, v166, v167
	v_cvt_pk_bf16_f32 v105, v164, v165
	v_cvt_pk_bf16_f32 v107, v160, v161
	s_nop 0
	v_cvt_pk_bf16_f32 v106, v162, v163
	global_store_dwordx4 v[118:119], v[104:107], off
	ds_read_b32 v114, v138 offset:4288
	v_ashrrev_i32_e32 v125, 31, v124
	v_lshlrev_b64 v[104:105], 11, v[124:125]
	v_lshl_add_u64 v[104:105], s[0:1], 0, v[104:105]
	v_lshl_add_u64 v[110:111], v[104:105], 0, v[148:149]
	v_add_u32_e32 v104, 0x80, v152
	v_mov_b32_e32 v116, v104
	s_waitcnt lgkmcnt(0)
	v_pk_mul_f32 v[100:101], v[100:101], v[114:115] op_sel_hi:[1,0]
	v_pk_mul_f32 v[102:103], v[102:103], v[114:115] op_sel_hi:[1,0]
	v_pk_mul_f32 v[96:97], v[96:97], v[114:115] op_sel_hi:[1,0]
	v_pk_mul_f32 v[98:99], v[98:99], v[114:115] op_sel_hi:[1,0]
	v_lshlrev_b32_e32 v114, 16, v224
	v_and_b32_e32 v115, 0xffff0000, v224
	v_lshlrev_b32_e32 v106, 16, v225
	v_and_b32_e32 v107, 0xffff0000, v225
	v_lshlrev_b32_e32 v118, 16, v226
	v_and_b32_e32 v119, 0xffff0000, v226
	v_lshlrev_b32_e32 v108, 16, v227
	v_and_b32_e32 v109, 0xffff0000, v227
	v_pk_fma_f32 v[156:157], v[134:135], v[102:103], v[106:107]
	v_pk_fma_f32 v[158:159], v[132:133], v[100:101], v[114:115]
	v_pk_fma_f32 v[124:125], v[130:131], v[98:99], v[108:109]
	v_pk_fma_f32 v[126:127], v[128:129], v[96:97], v[118:119]
	v_cvt_pk_bf16_f32 v96, v158, v159
	v_cvt_pk_bf16_f32 v97, v156, v157
	v_cvt_pk_bf16_f32 v99, v124, v125
	s_nop 0
	v_cvt_pk_bf16_f32 v98, v126, v127
	global_store_dwordx4 v[110:111], v[96:99], off
	ds_read_b32 v106, v138 offset:4608
	v_ashrrev_i32_e32 v117, 31, v116
	v_lshlrev_b64 v[96:97], 11, v[116:117]
	v_lshl_add_u64 v[96:97], s[0:1], 0, v[96:97]
	v_lshl_add_u64 v[102:103], v[96:97], 0, v[148:149]
	v_add_u32_e32 v96, 0x90, v152
	v_mov_b32_e32 v108, v96
	s_waitcnt lgkmcnt(0)
	v_pk_mul_f32 v[92:93], v[92:93], v[106:107] op_sel_hi:[1,0]
	v_pk_mul_f32 v[94:95], v[94:95], v[106:107] op_sel_hi:[1,0]
	v_pk_mul_f32 v[88:89], v[88:89], v[106:107] op_sel_hi:[1,0]
	v_pk_mul_f32 v[90:91], v[90:91], v[106:107] op_sel_hi:[1,0]
	v_lshlrev_b32_e32 v106, 16, v228
	v_and_b32_e32 v107, 0xffff0000, v228
	v_lshlrev_b32_e32 v98, 16, v229
	v_and_b32_e32 v99, 0xffff0000, v229
	v_lshlrev_b32_e32 v110, 16, v230
	v_and_b32_e32 v111, 0xffff0000, v230
	v_lshlrev_b32_e32 v100, 16, v231
	v_and_b32_e32 v101, 0xffff0000, v231
	v_pk_fma_f32 v[118:119], v[134:135], v[94:95], v[98:99]
	v_pk_fma_f32 v[122:123], v[132:133], v[92:93], v[106:107]
	v_pk_fma_f32 v[114:115], v[130:131], v[90:91], v[100:101]
	v_pk_fma_f32 v[116:117], v[128:129], v[88:89], v[110:111]
	v_cvt_pk_bf16_f32 v88, v122, v123
	v_cvt_pk_bf16_f32 v89, v118, v119
	v_cvt_pk_bf16_f32 v91, v114, v115
	s_nop 0
	v_cvt_pk_bf16_f32 v90, v116, v117
	global_store_dwordx4 v[102:103], v[88:91], off
	ds_read_b32 v94, v138 offset:4672
	v_ashrrev_i32_e32 v109, 31, v108
	v_lshlrev_b64 v[88:89], 11, v[108:109]
	v_lshl_add_u64 v[88:89], s[0:1], 0, v[88:89]
	v_lshl_add_u64 v[98:99], v[88:89], 0, v[148:149]
	v_add_u32_e32 v88, 0xa0, v152
	v_mov_b32_e32 v100, v88
	s_waitcnt lgkmcnt(0)
;   __device__ __forceinline__ bf16* h() const { unsigned o_ = (unsigned)(OFF_h); asm volatile("" : "+s"(o_)); return (bf16*)(ws + o_); }
;   __device__ __forceinline__ bf16* y() const { unsigned o_ = (unsigned)(OFF_y); asm volatile("" : "+s"(o_)); return (bf16*)(ws + o_); }
; __device__ __forceinline__ unsigned pk2(float a, float b) { unsigned r; asm("v_cvt_pk_bf16_f32 %0, %1, %2" : "=v"(r) : "v"(a), "v"(b)); return r; }
; __device__ __forceinline__ float lo16(unsigned v) { return __uint_as_float(v << 16); }
; __device__ __forceinline__ float hi16(unsigned v) { return __uint_as_float(v & 0xffff0000u); }
;   __device__ __forceinline__ void fused(f32x4 (&acc)[2][2][4][2], const pg8::Unit& u, int wr, int wc, int fr, int fq, PG8_LAS unsigned char* lds, int wid,
;                                         int lane) const {
;     ...
;       for (int ai = 0; ai < 2; ++ai)
; #pragma unroll
;         for (int m = 0; m < 4; ++m) {
;           const int rl = ai * 128 + wr * 64 + m * 16 + fr;
;           int r = u.pm * 256 + rl;
;           asm volatile("" : "+v"(r));
;           const float rs = rsv[rl];
;           const uint4 hb_ = *(const uint4*)(h + (size_t)r * D + c);
;           const f32x4 hv0 = f32x4{lo16(hb_.x), hi16(hb_.x), lo16(hb_.y), hi16(hb_.y)};
;           const f32x4 hv1 = f32x4{lo16(hb_.z), hi16(hb_.z), lo16(hb_.w), hi16(hb_.w)};
;           const f32x4 nv0 = hv0 + acc[ai][bj][m][0] * rs * gp0;
;           const f32x4 nv1 = hv1 + acc[ai][bj][m][1] * rs * gp1;
;           acc[ai][bj][m][0] = nv0; acc[ai][bj][m][1] = nv1;
;           if (!LAST) {
;             uint4 ho_; ho_.x = pk2(nv0[0], nv0[1]); ho_.y = pk2(nv0[2], nv0[3]); ho_.z = pk2(nv1[0], nv1[1]); ho_.w = pk2(nv1[2], nv1[3]);
;             *(uint4*)(h + (size_t)r * D + c) = ho_;
	v_pk_mul_f32 v[84:85], v[84:85], v[94:95] op_sel_hi:[1,0]
	v_pk_mul_f32 v[86:87], v[86:87], v[94:95] op_sel_hi:[1,0]
	v_pk_mul_f32 v[80:81], v[80:81], v[94:95] op_sel_hi:[1,0]
	v_pk_mul_f32 v[82:83], v[82:83], v[94:95] op_sel_hi:[1,0]
	v_lshlrev_b32_e32 v94, 16, v232
	v_and_b32_e32 v95, 0xffff0000, v232
	v_lshlrev_b32_e32 v90, 16, v233
	v_and_b32_e32 v91, 0xffff0000, v233
	v_lshlrev_b32_e32 v102, 16, v234
	v_and_b32_e32 v103, 0xffff0000, v234
	v_lshlrev_b32_e32 v92, 16, v235
	v_and_b32_e32 v93, 0xffff0000, v235
	v_pk_fma_f32 v[86:87], v[134:135], v[86:87], v[90:91]
	v_pk_fma_f32 v[90:91], v[132:133], v[84:85], v[94:95]
	v_pk_fma_f32 v[82:83], v[130:131], v[82:83], v[92:93]
	v_pk_fma_f32 v[84:85], v[128:129], v[80:81], v[102:103]
	v_cvt_pk_bf16_f32 v92, v90, v91
	v_cvt_pk_bf16_f32 v93, v86, v87
	v_cvt_pk_bf16_f32 v95, v82, v83
	s_nop 0
	v_cvt_pk_bf16_f32 v94, v84, v85
	global_store_dwordx4 v[98:99], v[92:95], off
	s_nop 0
	v_ashrrev_i32_e32 v101, 31, v100
	v_lshlrev_b64 v[80:81], 11, v[100:101]
	v_lshl_add_u64 v[80:81], s[0:1], 0, v[80:81]
	v_lshl_add_u64 v[98:99], v[80:81], 0, v[148:149]
	ds_read_b32 v100, v138 offset:4736
	v_add_u32_e32 v80, 0xb0, v152
	v_mov_b32_e32 v102, v80
	s_waitcnt lgkmcnt(0)
	v_pk_mul_f32 v[106:107], v[76:77], v[100:101] op_sel_hi:[1,0]
	v_pk_mul_f32 v[76:77], v[78:79], v[100:101] op_sel_hi:[1,0]
	v_pk_mul_f32 v[108:109], v[72:73], v[100:101] op_sel_hi:[1,0]
	v_pk_mul_f32 v[72:73], v[74:75], v[100:101] op_sel_hi:[1,0]
	v_lshlrev_b32_e32 v74, 16, v236
	v_and_b32_e32 v75, 0xffff0000, v236
	v_lshlrev_b32_e32 v78, 16, v237
	v_and_b32_e32 v79, 0xffff0000, v237
	v_lshlrev_b32_e32 v92, 16, v238
	v_and_b32_e32 v93, 0xffff0000, v238
	v_lshlrev_b32_e32 v94, 16, v239
	v_and_b32_e32 v95, 0xffff0000, v239
	v_pk_fma_f32 v[76:77], v[134:135], v[76:77], v[78:79]
	v_pk_fma_f32 v[78:79], v[132:133], v[106:107], v[74:75]
	v_pk_fma_f32 v[72:73], v[130:131], v[72:73], v[94:95]
	v_pk_fma_f32 v[74:75], v[128:129], v[108:109], v[92:93]
	v_cvt_pk_bf16_f32 v92, v78, v79
	v_cvt_pk_bf16_f32 v93, v76, v77
	v_cvt_pk_bf16_f32 v95, v72, v73
	v_mov_b32_e32 v106, v152
	v_cvt_pk_bf16_f32 v94, v74, v75
	global_store_dwordx4 v[98:99], v[92:95], off
	ds_read_b32 v98, v138 offset:4800
	v_ashrrev_i32_e32 v103, 31, v102
	v_lshlrev_b64 v[92:93], 11, v[102:103]
	v_lshl_add_u64 v[92:93], s[0:1], 0, v[92:93]
	v_lshl_add_u64 v[102:103], v[92:93], 0, v[148:149]
	s_waitcnt lgkmcnt(0)
	v_pk_mul_f32 v[68:69], v[68:69], v[98:99] op_sel_hi:[1,0]
	v_pk_mul_f32 v[70:71], v[70:71], v[98:99] op_sel_hi:[1,0]
	v_pk_mul_f32 v[64:65], v[64:65], v[98:99] op_sel_hi:[1,0]
	v_pk_mul_f32 v[66:67], v[66:67], v[98:99] op_sel_hi:[1,0]
	v_lshlrev_b32_e32 v100, 16, v240
	v_and_b32_e32 v101, 0xffff0000, v240
	v_lshlrev_b32_e32 v92, 16, v241
	v_and_b32_e32 v93, 0xffff0000, v241
	v_lshlrev_b32_e32 v108, 16, v242
	v_and_b32_e32 v109, 0xffff0000, v242
	v_lshlrev_b32_e32 v94, 16, v243
	v_and_b32_e32 v95, 0xffff0000, v243
	v_pk_fma_f32 v[98:99], v[134:135], v[70:71], v[92:93]
	v_pk_fma_f32 v[100:101], v[132:133], v[68:69], v[100:101]
	v_pk_fma_f32 v[92:93], v[130:131], v[66:67], v[94:95]
	v_pk_fma_f32 v[94:95], v[128:129], v[64:65], v[108:109]
	v_cvt_pk_bf16_f32 v64, v100, v101
	v_cvt_pk_bf16_f32 v65, v98, v99
	v_cvt_pk_bf16_f32 v67, v92, v93
	v_mov_b32_e32 v130, v150
	v_cvt_pk_bf16_f32 v66, v94, v95
	global_store_dwordx4 v[102:103], v[64:67], off
	global_load_dwordx4 v[64:67], v[186:187], off offset:528
	s_nop 0
	global_load_dwordx4 v[68:71], v[186:187], off offset:512
	s_nop 0
	v_ashrrev_i32_e32 v107, 31, v106
	v_lshlrev_b64 v[102:103], 11, v[106:107]
	v_lshl_add_u64 v[102:103], s[0:1], 0, v[102:103]
	v_lshl_add_u64 v[128:129], v[102:103], 0, v[148:149]
	v_mov_b32_e32 v244, v152
	v_ashrrev_i32_e32 v245, 31, v244
	v_lshlrev_b64 v[244:245], 11, v[244:245]
	v_lshl_add_u64 v[244:245], s[0:1], 0, v[244:245]
	v_lshl_add_u64 v[244:245], v[244:245], 0, v[148:149]
	global_load_dwordx4 v[212:215], v[244:245], off offset:256
	v_add_u32_e32 v244, 0x10, v152
	v_ashrrev_i32_e32 v245, 31, v244
	v_lshlrev_b64 v[244:245], 11, v[244:245]
	v_lshl_add_u64 v[244:245], s[0:1], 0, v[244:245]
	v_lshl_add_u64 v[244:245], v[244:245], 0, v[148:149]
	global_load_dwordx4 v[216:219], v[244:245], off offset:256
	v_add_u32_e32 v244, 0x20, v152
	v_ashrrev_i32_e32 v245, 31, v244
	v_lshlrev_b64 v[244:245], 11, v[244:245]
	v_lshl_add_u64 v[244:245], s[0:1], 0, v[244:245]
	v_lshl_add_u64 v[244:245], v[244:245], 0, v[148:149]
	global_load_dwordx4 v[220:223], v[244:245], off offset:256
	v_add_u32_e32 v244, 0x30, v152
	v_ashrrev_i32_e32 v245, 31, v244
	v_lshlrev_b64 v[244:245], 11, v[244:245]
	v_lshl_add_u64 v[244:245], s[0:1], 0, v[244:245]
	v_lshl_add_u64 v[244:245], v[244:245], 0, v[148:149]
	global_load_dwordx4 v[224:227], v[244:245], off offset:256
	v_add_u32_e32 v244, 0x80, v152
	v_ashrrev_i32_e32 v245, 31, v244
	v_lshlrev_b64 v[244:245], 11, v[244:245]
	v_lshl_add_u64 v[244:245], s[0:1], 0, v[244:245]
	v_lshl_add_u64 v[244:245], v[244:245], 0, v[148:149]
	global_load_dwordx4 v[228:231], v[244:245], off offset:256
	v_add_u32_e32 v244, 0x90, v152
	v_ashrrev_i32_e32 v245, 31, v244
	v_lshlrev_b64 v[244:245], 11, v[244:245]
	v_lshl_add_u64 v[244:245], s[0:1], 0, v[244:245]
	v_lshl_add_u64 v[244:245], v[244:245], 0, v[148:149]
	global_load_dwordx4 v[232:235], v[244:245], off offset:256
	v_add_u32_e32 v244, 0xa0, v152
	v_ashrrev_i32_e32 v245, 31, v244
	v_lshlrev_b64 v[244:245], 11, v[244:245]
	v_lshl_add_u64 v[244:245], s[0:1], 0, v[244:245]
	v_lshl_add_u64 v[244:245], v[244:245], 0, v[148:149]
	global_load_dwordx4 v[236:239], v[244:245], off offset:256
	v_add_u32_e32 v244, 0xb0, v152
	v_ashrrev_i32_e32 v245, 31, v244
	v_lshlrev_b64 v[244:245], 11, v[244:245]
	v_lshl_add_u64 v[244:245], s[0:1], 0, v[244:245]
	v_lshl_add_u64 v[244:245], v[244:245], 0, v[148:149]
	global_load_dwordx4 v[240:243], v[244:245], off offset:256
	ds_read_b32 v102, v138 offset:4096
	s_waitcnt lgkmcnt(0)
;   __device__ __forceinline__ bf16* h() const { unsigned o_ = (unsigned)(OFF_h); asm volatile("" : "+s"(o_)); return (bf16*)(ws + o_); }
;   __device__ __forceinline__ bf16* y() const { unsigned o_ = (unsigned)(OFF_y); asm volatile("" : "+s"(o_)); return (bf16*)(ws + o_); }
; __device__ __forceinline__ unsigned pk2(float a, float b) { unsigned r; asm("v_cvt_pk_bf16_f32 %0, %1, %2" : "=v"(r) : "v"(a), "v"(b)); return r; }
; __device__ __forceinline__ float lo16(unsigned v) { return __uint_as_float(v << 16); }
; __device__ __forceinline__ float hi16(unsigned v) { return __uint_as_float(v & 0xffff0000u); }
;   __device__ __forceinline__ void fused(f32x4 (&acc)[2][2][4][2], const pg8::Unit& u, int wr, int wc, int fr, int fq, PG8_LAS unsigned char* lds, int wid,
;                                         int lane) const {
;     ...
;       for (int ai = 0; ai < 2; ++ai)
; #pragma unroll
;         for (int m = 0; m < 4; ++m) {
;           const int rl = ai * 128 + wr * 64 + m * 16 + fr;
;           int r = u.pm * 256 + rl;
;           asm volatile("" : "+v"(r));
;           const float rs = rsv[rl];
;           const uint4 hb_ = *(const uint4*)(h + (size_t)r * D + c);
;           const f32x4 hv0 = f32x4{lo16(hb_.x), hi16(hb_.x), lo16(hb_.y), hi16(hb_.y)};
;           const f32x4 hv1 = f32x4{lo16(hb_.z), hi16(hb_.z), lo16(hb_.w), hi16(hb_.w)};
;           const f32x4 nv0 = hv0 + acc[ai][bj][m][0] * rs * gp0;
;           const f32x4 nv1 = hv1 + acc[ai][bj][m][1] * rs * gp1;
;           acc[ai][bj][m][0] = nv0; acc[ai][bj][m][1] = nv1;
;           if (!LAST) {
;             uint4 ho_; ho_.x = pk2(nv0[0], nv0[1]); ho_.y = pk2(nv0[2], nv0[3]); ho_.z = pk2(nv1[0], nv1[1]); ho_.w = pk2(nv1[2], nv1[3]);
;             *(uint4*)(h + (size_t)r * D + c) = ho_;
	v_pk_mul_f32 v[60:61], v[60:61], v[102:103] op_sel_hi:[1,0]
	v_pk_mul_f32 v[62:63], v[62:63], v[102:103] op_sel_hi:[1,0]
	v_pk_mul_f32 v[56:57], v[56:57], v[102:103] op_sel_hi:[1,0]
	v_pk_mul_f32 v[58:59], v[58:59], v[102:103] op_sel_hi:[1,0]
	s_waitcnt vmcnt(0)
	v_lshlrev_b32_e32 v102, 16, v212
	v_and_b32_e32 v103, 0xffff0000, v212
	v_lshlrev_b32_e32 v106, 16, v213
	v_and_b32_e32 v107, 0xffff0000, v213
	v_lshlrev_b32_e32 v132, 16, v214
	v_and_b32_e32 v133, 0xffff0000, v214
	v_lshlrev_b32_e32 v134, 16, v215
	v_and_b32_e32 v135, 0xffff0000, v215
	v_pk_fma_f32 v[108:109], v[70:71], v[62:63], v[106:107]
	v_pk_fma_f32 v[110:111], v[68:69], v[60:61], v[102:103]
	v_pk_fma_f32 v[102:103], v[66:67], v[58:59], v[134:135]
	v_pk_fma_f32 v[106:107], v[64:65], v[56:57], v[132:133]
	v_cvt_pk_bf16_f32 v56, v110, v111
	v_cvt_pk_bf16_f32 v57, v108, v109
	v_cvt_pk_bf16_f32 v59, v102, v103
	s_nop 0
	v_cvt_pk_bf16_f32 v58, v106, v107
	global_store_dwordx4 v[128:129], v[56:59], off offset:256
	ds_read_b32 v60, v138 offset:4160
	v_ashrrev_i32_e32 v131, 31, v130
	v_lshlrev_b64 v[56:57], 11, v[130:131]
	v_lshl_add_u64 v[56:57], s[0:1], 0, v[56:57]
	v_lshl_add_u64 v[128:129], v[56:57], 0, v[148:149]
	v_mov_b32_e32 v130, v120
	s_waitcnt lgkmcnt(0)
	v_pk_mul_f32 v[52:53], v[52:53], v[60:61] op_sel_hi:[1,0]
	v_pk_mul_f32 v[54:55], v[54:55], v[60:61] op_sel_hi:[1,0]
	v_pk_mul_f32 v[48:49], v[48:49], v[60:61] op_sel_hi:[1,0]
	v_pk_mul_f32 v[50:51], v[50:51], v[60:61] op_sel_hi:[1,0]
	v_lshlrev_b32_e32 v62, 16, v216
	v_and_b32_e32 v63, 0xffff0000, v216
	v_lshlrev_b32_e32 v56, 16, v217
	v_and_b32_e32 v57, 0xffff0000, v217
	v_lshlrev_b32_e32 v132, 16, v218
	v_and_b32_e32 v133, 0xffff0000, v218
	v_lshlrev_b32_e32 v58, 16, v219
	v_and_b32_e32 v59, 0xffff0000, v219
	v_pk_fma_f32 v[60:61], v[70:71], v[54:55], v[56:57]
	v_pk_fma_f32 v[62:63], v[68:69], v[52:53], v[62:63]
	v_pk_fma_f32 v[56:57], v[66:67], v[50:51], v[58:59]
	v_pk_fma_f32 v[58:59], v[64:65], v[48:49], v[132:133]
	v_cvt_pk_bf16_f32 v48, v62, v63
	v_cvt_pk_bf16_f32 v49, v60, v61
	v_cvt_pk_bf16_f32 v51, v56, v57
	s_nop 0
	v_cvt_pk_bf16_f32 v50, v58, v59
	global_store_dwordx4 v[128:129], v[48:51], off offset:256
	ds_read_b32 v54, v138 offset:4224
	v_ashrrev_i32_e32 v131, 31, v130
	v_lshlrev_b64 v[48:49], 11, v[130:131]
	v_lshl_add_u64 v[48:49], s[0:1], 0, v[48:49]
	v_lshl_add_u64 v[52:53], v[48:49], 0, v[148:149]
	v_mov_b32_e32 v128, v112
	s_waitcnt lgkmcnt(0)
	v_pk_mul_f32 v[130:131], v[44:45], v[54:55] op_sel_hi:[1,0]
	v_pk_mul_f32 v[44:45], v[46:47], v[54:55] op_sel_hi:[1,0]
	v_pk_mul_f32 v[132:133], v[40:41], v[54:55] op_sel_hi:[1,0]
	v_pk_mul_f32 v[40:41], v[42:43], v[54:55] op_sel_hi:[1,0]
	v_lshlrev_b32_e32 v42, 16, v220
	v_and_b32_e32 v43, 0xffff0000, v220
	v_lshlrev_b32_e32 v46, 16, v221
	v_and_b32_e32 v47, 0xffff0000, v221
	v_lshlrev_b32_e32 v48, 16, v222
	v_and_b32_e32 v49, 0xffff0000, v222
	v_lshlrev_b32_e32 v50, 16, v223
	v_and_b32_e32 v51, 0xffff0000, v223
	v_pk_fma_f32 v[44:45], v[70:71], v[44:45], v[46:47]
	v_pk_fma_f32 v[46:47], v[68:69], v[130:131], v[42:43]
	v_pk_fma_f32 v[40:41], v[66:67], v[40:41], v[50:51]
	v_pk_fma_f32 v[42:43], v[64:65], v[132:133], v[48:49]
	v_cvt_pk_bf16_f32 v48, v46, v47
	v_cvt_pk_bf16_f32 v49, v44, v45
	v_cvt_pk_bf16_f32 v51, v40, v41
	s_nop 0
	v_cvt_pk_bf16_f32 v50, v42, v43
	global_store_dwordx4 v[52:53], v[48:51], off offset:256
	ds_read_b32 v54, v138 offset:4288
	v_ashrrev_i32_e32 v129, 31, v128
	v_lshlrev_b64 v[48:49], 11, v[128:129]
	v_lshl_add_u64 v[48:49], s[0:1], 0, v[48:49]
	v_lshl_add_u64 v[52:53], v[48:49], 0, v[148:149]
	v_mov_b32_e32 v128, v104
	s_waitcnt lgkmcnt(0)
	v_pk_mul_f32 v[130:131], v[36:37], v[54:55] op_sel_hi:[1,0]
	v_pk_mul_f32 v[36:37], v[38:39], v[54:55] op_sel_hi:[1,0]
	v_pk_mul_f32 v[132:133], v[32:33], v[54:55] op_sel_hi:[1,0]
	v_pk_mul_f32 v[32:33], v[34:35], v[54:55] op_sel_hi:[1,0]
	v_lshlrev_b32_e32 v34, 16, v224
	v_and_b32_e32 v35, 0xffff0000, v224
	v_lshlrev_b32_e32 v38, 16, v225
	v_and_b32_e32 v39, 0xffff0000, v225
	v_lshlrev_b32_e32 v48, 16, v226
	v_and_b32_e32 v49, 0xffff0000, v226
	v_lshlrev_b32_e32 v50, 16, v227
	v_and_b32_e32 v51, 0xffff0000, v227
	v_pk_fma_f32 v[36:37], v[70:71], v[36:37], v[38:39]
	v_pk_fma_f32 v[38:39], v[68:69], v[130:131], v[34:35]
	v_pk_fma_f32 v[32:33], v[66:67], v[32:33], v[50:51]
	v_pk_fma_f32 v[34:35], v[64:65], v[132:133], v[48:49]
	v_cvt_pk_bf16_f32 v48, v38, v39
	v_cvt_pk_bf16_f32 v49, v36, v37
	v_cvt_pk_bf16_f32 v51, v32, v33
	s_nop 0
	v_cvt_pk_bf16_f32 v50, v34, v35
	global_store_dwordx4 v[52:53], v[48:51], off offset:256
	ds_read_b32 v54, v138 offset:4608
	v_ashrrev_i32_e32 v129, 31, v128
	v_lshlrev_b64 v[48:49], 11, v[128:129]
	v_lshl_add_u64 v[48:49], s[0:1], 0, v[48:49]
	v_lshl_add_u64 v[52:53], v[48:49], 0, v[148:149]
	v_mov_b32_e32 v128, v96
	s_waitcnt lgkmcnt(0)
	v_pk_mul_f32 v[130:131], v[28:29], v[54:55] op_sel_hi:[1,0]
	v_pk_mul_f32 v[28:29], v[30:31], v[54:55] op_sel_hi:[1,0]
	v_pk_mul_f32 v[24:25], v[24:25], v[54:55] op_sel_hi:[1,0]
	v_pk_mul_f32 v[26:27], v[26:27], v[54:55] op_sel_hi:[1,0]
	v_lshlrev_b32_e32 v30, 16, v228
	v_and_b32_e32 v31, 0xffff0000, v228
	v_lshlrev_b32_e32 v48, 16, v229
	v_and_b32_e32 v49, 0xffff0000, v229
	v_lshlrev_b32_e32 v54, 16, v230
	v_and_b32_e32 v55, 0xffff0000, v230
	v_lshlrev_b32_e32 v50, 16, v231
	v_and_b32_e32 v51, 0xffff0000, v231
	v_pk_fma_f32 v[28:29], v[70:71], v[28:29], v[48:49]
	v_pk_fma_f32 v[30:31], v[68:69], v[130:131], v[30:31]
	v_pk_fma_f32 v[26:27], v[66:67], v[26:27], v[50:51]
	v_pk_fma_f32 v[24:25], v[64:65], v[24:25], v[54:55]
	v_cvt_pk_bf16_f32 v48, v30, v31
	v_cvt_pk_bf16_f32 v49, v28, v29
	v_cvt_pk_bf16_f32 v51, v26, v27
	s_nop 0
	v_cvt_pk_bf16_f32 v50, v24, v25
	global_store_dwordx4 v[52:53], v[48:51], off offset:256
	ds_read_b32 v54, v138 offset:4672
	v_ashrrev_i32_e32 v129, 31, v128
	v_lshlrev_b64 v[48:49], 11, v[128:129]
	v_lshl_add_u64 v[48:49], s[0:1], 0, v[48:49]
	v_lshl_add_u64 v[52:53], v[48:49], 0, v[148:149]
	v_mov_b32_e32 v128, v88
	s_waitcnt lgkmcnt(0)
;   __device__ __forceinline__ bf16* h() const { unsigned o_ = (unsigned)(OFF_h); asm volatile("" : "+s"(o_)); return (bf16*)(ws + o_); }
;   __device__ __forceinline__ bf16* y() const { unsigned o_ = (unsigned)(OFF_y); asm volatile("" : "+s"(o_)); return (bf16*)(ws + o_); }
; __device__ __forceinline__ unsigned pk2(float a, float b) { unsigned r; asm("v_cvt_pk_bf16_f32 %0, %1, %2" : "=v"(r) : "v"(a), "v"(b)); return r; }
;   __device__ __forceinline__ void exchange(const f32x4 (&acc)[2][2][4][2], const pg8::Unit& u, int wr, int wc, int fr, int fq, PG8_LAS float* ssq,
;                                            PG8_LAS float* rsv, int tid, float* ex, unsigned* cnt) const {
; #pragma unroll
;     for (int ai = 0; ai < 2; ++ai)
; #pragma unroll
;       for (int m = 0; m < 4; ++m) {
;         float sv = 0.f;
; #pragma unroll
;         for (int bj = 0; bj < 2; ++bj)
; #pragma unroll
;           for (int n = 0; n < 2; ++n) {
;             const f32x4 a = acc[ai][bj][m][n];
;             sv += a[0] * a[0] + a[1] * a[1] + a[2] * a[2] + a[3] * a[3];
;           }
;         sv += __shfl_xor(sv, 16); sv += __shfl_xor(sv, 32);
;         if (fq == 0) ssq[wc * 256 + ai * 128 + wr * 64 + m * 16 + fr] = sv;
;       }
;   __device__ __forceinline__ void fused(f32x4 (&acc)[2][2][4][2], const pg8::Unit& u, int wr, int wc, int fr, int fq, PG8_LAS unsigned char* lds, int wid,
;                                         int lane) const {
;     ...
;       for (int ai = 0; ai < 2; ++ai)
; #pragma unroll
;         for (int m = 0; m < 4; ++m) {
;           const int rl = ai * 128 + wr * 64 + m * 16 + fr;
;           int r = u.pm * 256 + rl;
;           asm volatile("" : "+v"(r));
;           const float rs = rsv[rl];
;           const uint4 hb_ = *(const uint4*)(h + (size_t)r * D + c);
;           const f32x4 hv0 = f32x4{lo16(hb_.x), hi16(hb_.x), lo16(hb_.y), hi16(hb_.y)};
;           const f32x4 hv1 = f32x4{lo16(hb_.z), hi16(hb_.z), lo16(hb_.w), hi16(hb_.w)};
;           const f32x4 nv0 = hv0 + acc[ai][bj][m][0] * rs * gp0;
;           const f32x4 nv1 = hv1 + acc[ai][bj][m][1] * rs * gp1;
;           acc[ai][bj][m][0] = nv0; acc[ai][bj][m][1] = nv1;
;           if (!LAST) {
;             uint4 ho_; ho_.x = pk2(nv0[0], nv0[1]); ho_.y = pk2(nv0[2], nv0[3]); ho_.z = pk2(nv1[0], nv1[1]); ho_.w = pk2(nv1[2], nv1[3]);
;             *(uint4*)(h + (size_t)r * D + c) = ho_;
	v_pk_mul_f32 v[130:131], v[20:21], v[54:55] op_sel_hi:[1,0]
	v_pk_mul_f32 v[20:21], v[22:23], v[54:55] op_sel_hi:[1,0]
	v_pk_mul_f32 v[132:133], v[16:17], v[54:55] op_sel_hi:[1,0]
	v_pk_mul_f32 v[16:17], v[18:19], v[54:55] op_sel_hi:[1,0]
	v_lshlrev_b32_e32 v18, 16, v232
	v_and_b32_e32 v19, 0xffff0000, v232
	v_lshlrev_b32_e32 v22, 16, v233
	v_and_b32_e32 v23, 0xffff0000, v233
	v_lshlrev_b32_e32 v48, 16, v234
	v_and_b32_e32 v49, 0xffff0000, v234
	v_lshlrev_b32_e32 v50, 16, v235
	v_and_b32_e32 v51, 0xffff0000, v235
	v_pk_fma_f32 v[20:21], v[70:71], v[20:21], v[22:23]
	v_pk_fma_f32 v[22:23], v[68:69], v[130:131], v[18:19]
	v_pk_fma_f32 v[16:17], v[66:67], v[16:17], v[50:51]
	v_pk_fma_f32 v[18:19], v[64:65], v[132:133], v[48:49]
	v_cvt_pk_bf16_f32 v48, v22, v23
	v_cvt_pk_bf16_f32 v49, v20, v21
	v_cvt_pk_bf16_f32 v51, v16, v17
	s_nop 0
	v_cvt_pk_bf16_f32 v50, v18, v19
	global_store_dwordx4 v[52:53], v[48:51], off offset:256
	ds_read_b32 v54, v138 offset:4736
	v_ashrrev_i32_e32 v129, 31, v128
	v_lshlrev_b64 v[48:49], 11, v[128:129]
	v_lshl_add_u64 v[48:49], s[0:1], 0, v[48:49]
	v_lshl_add_u64 v[52:53], v[48:49], 0, v[148:149]
	v_mov_b32_e32 v128, v80
	s_waitcnt lgkmcnt(0)
	v_pk_mul_f32 v[130:131], v[12:13], v[54:55] op_sel_hi:[1,0]
	v_pk_mul_f32 v[12:13], v[14:15], v[54:55] op_sel_hi:[1,0]
	v_pk_mul_f32 v[132:133], v[8:9], v[54:55] op_sel_hi:[1,0]
	v_pk_mul_f32 v[8:9], v[10:11], v[54:55] op_sel_hi:[1,0]
	v_mul_f32_e32 v54, v107, v107
	v_fmac_f32_e32 v54, v106, v106
	v_fmac_f32_e32 v54, v102, v102
	v_fmac_f32_e32 v54, v103, v103
	v_lshlrev_b32_e32 v10, 16, v236
	v_and_b32_e32 v11, 0xffff0000, v236
	v_lshlrev_b32_e32 v14, 16, v237
	v_and_b32_e32 v15, 0xffff0000, v237
	v_lshlrev_b32_e32 v48, 16, v238
	v_and_b32_e32 v49, 0xffff0000, v238
	v_lshlrev_b32_e32 v50, 16, v239
	v_and_b32_e32 v51, 0xffff0000, v239
	v_pk_fma_f32 v[12:13], v[70:71], v[12:13], v[14:15]
	v_pk_fma_f32 v[14:15], v[68:69], v[130:131], v[10:11]
	v_pk_fma_f32 v[8:9], v[66:67], v[8:9], v[50:51]
	v_pk_fma_f32 v[10:11], v[64:65], v[132:133], v[48:49]
	v_cvt_pk_bf16_f32 v48, v14, v15
	v_cvt_pk_bf16_f32 v49, v12, v13
	v_cvt_pk_bf16_f32 v51, v8, v9
	s_nop 0
	v_cvt_pk_bf16_f32 v50, v10, v11
	global_store_dwordx4 v[52:53], v[48:51], off offset:256
	v_mul_f32_e32 v52, v185, v185
	v_ashrrev_i32_e32 v129, 31, v128
	v_lshlrev_b64 v[48:49], 11, v[128:129]
	v_lshl_add_u64 v[48:49], s[0:1], 0, v[48:49]
	v_lshl_add_u64 v[128:129], v[48:49], 0, v[148:149]
	v_mul_f32_e32 v53, v181, v181
	v_fmac_f32_e32 v52, v184, v184
	v_fmac_f32_e32 v53, v180, v180
	v_fmac_f32_e32 v52, v182, v182
	v_fmac_f32_e32 v53, v178, v178
	v_fmac_f32_e32 v52, v183, v183
	v_fmac_f32_e32 v53, v179, v179
	v_add_f32_e32 v52, v52, v53
	v_mul_f32_e32 v53, v111, v111
	v_fmac_f32_e32 v53, v110, v110
	v_fmac_f32_e32 v53, v108, v108
	v_fmac_f32_e32 v53, v109, v109
	v_add_f32_e32 v52, v52, v53
	v_add_f32_e32 v53, v52, v54
	ds_bpermute_b32 v54, v151, v53
	ds_read_b32 v52, v138 offset:4800
	s_waitcnt lgkmcnt(1)
	v_add_f32_e32 v81, v53, v54
	ds_bpermute_b32 v89, v209, v81
	s_waitcnt lgkmcnt(1)
	v_pk_mul_f32 v[4:5], v[4:5], v[52:53] op_sel_hi:[1,0]
	v_pk_mul_f32 v[6:7], v[6:7], v[52:53] op_sel_hi:[1,0]
	v_pk_mul_f32 v[0:1], v[0:1], v[52:53] op_sel_hi:[1,0]
	v_pk_mul_f32 v[2:3], v[2:3], v[52:53] op_sel_hi:[1,0]
	v_lshlrev_b32_e32 v54, 16, v240
	v_and_b32_e32 v55, 0xffff0000, v240
	v_lshlrev_b32_e32 v48, 16, v241
	v_and_b32_e32 v49, 0xffff0000, v241
	v_lshlrev_b32_e32 v130, 16, v242
	v_and_b32_e32 v131, 0xffff0000, v242
	v_lshlrev_b32_e32 v50, 16, v243
	v_and_b32_e32 v51, 0xffff0000, v243
	v_pk_fma_f32 v[52:53], v[70:71], v[6:7], v[48:49]
	v_pk_fma_f32 v[54:55], v[68:69], v[4:5], v[54:55]
	v_pk_fma_f32 v[48:49], v[66:67], v[2:3], v[50:51]
	v_pk_fma_f32 v[50:51], v[64:65], v[0:1], v[130:131]
	v_cvt_pk_bf16_f32 v0, v54, v55
	v_cvt_pk_bf16_f32 v1, v52, v53
	v_cvt_pk_bf16_f32 v3, v48, v49
	s_nop 0
	v_cvt_pk_bf16_f32 v2, v50, v51
	global_store_dwordx4 v[128:129], v[0:3], off offset:256
	s_waitcnt lgkmcnt(0)
	s_barrier
	s_and_saveexec_b64 s[0:1], s[4:5]
	v_add_f32_e32 v0, v81, v89
	ds_write_b32 v153, v0
	s_or_b64 exec, exec, s[0:1]
	v_mul_f32_e32 v0, v177, v177
	v_mul_f32_e32 v1, v173, v173
	v_fmac_f32_e32 v0, v176, v176
	v_fmac_f32_e32 v1, v172, v172
	v_fmac_f32_e32 v0, v174, v174
	v_fmac_f32_e32 v1, v170, v170
	v_fmac_f32_e32 v0, v175, v175
	v_fmac_f32_e32 v1, v171, v171
	v_add_f32_e32 v0, v0, v1
	v_mul_f32_e32 v1, v63, v63
	v_fmac_f32_e32 v1, v62, v62
	v_fmac_f32_e32 v1, v60, v60
	v_fmac_f32_e32 v1, v61, v61
	v_add_f32_e32 v0, v0, v1
	v_mul_f32_e32 v1, v59, v59
	v_fmac_f32_e32 v1, v58, v58
	v_fmac_f32_e32 v1, v56, v56
	v_fmac_f32_e32 v1, v57, v57
	v_add_f32_e32 v0, v0, v1
	ds_bpermute_b32 v1, v151, v0
	s_waitcnt lgkmcnt(0)
	v_add_f32_e32 v0, v0, v1
	ds_bpermute_b32 v1, v209, v0
	s_and_saveexec_b64 s[0:1], s[4:5]
	s_cbranch_execz .LBB0_1116
	s_waitcnt lgkmcnt(0)
	v_add_f32_e32 v0, v0, v1
	ds_write_b32 v153, v0 offset:64
